# v91 + attention unit staging: K/V, rel-bias LUT, sink and Q-fragment loads issued back to back (one exposed latency per unit)
# speedup vs baseline: 1.0074x; 1.0074x over previous
.Lattn_body:
	ds_read_b128 v[48:51], v153
	ds_read_b128 v[52:55], v153 offset:64
	s_cmp_eq_u32 s20, 0
	s_cselect_b64 vcc, -1, 0
	s_mov_b32 s7, 0xf149f2ca
	s_mov_b32 s6, 0x3fb8aa3b
	v_lshl_add_u64 v[134:135], v[130:131], 0, s[0:1]
	s_add_i32 s20, s11, 1
	v_readlane_b32 s36, v252, 10
	v_readlane_b32 s37, v252, 11
	s_waitcnt vmcnt(15) lgkmcnt(1)
	v_mfma_f32_16x16x32_bf16 v[56:59], v[48:51], v[84:87], 0
	v_mul_f32_e32 v133, 0x3fb8aa3b, v162
	s_waitcnt vmcnt(13)
	v_mfma_f32_16x16x32_bf16 v[48:51], v[48:51], v[92:95], 0
	s_waitcnt lgkmcnt(0)
	v_mfma_f32_16x16x32_bf16 v[100:103], v[52:55], v[88:91], v[56:59]
	s_waitcnt vmcnt(12)
	v_mfma_f32_16x16x32_bf16 v[48:51], v[52:55], v[96:99], v[48:51]
	ds_read_b128 v[52:55], v153 offset:2304
	ds_read_b128 v[56:59], v153 offset:2368
	s_waitcnt lgkmcnt(1)
	v_mfma_f32_16x16x32_bf16 v[60:63], v[52:55], v[84:87], 0
	v_mfma_f32_16x16x32_bf16 v[52:55], v[52:55], v[92:95], 0
	s_waitcnt lgkmcnt(0)
	v_mfma_f32_16x16x32_bf16 v[104:107], v[56:59], v[88:91], v[60:63]
	v_mfma_f32_16x16x32_bf16 v[52:55], v[56:59], v[96:99], v[52:55]
	ds_read_b128 v[56:59], v153 offset:4608
	s_nop 2
	ds_read_b128 v[60:63], v153 offset:4672
	s_waitcnt lgkmcnt(1)
	v_mfma_f32_16x16x32_bf16 v[64:67], v[56:59], v[84:87], 0
	v_mfma_f32_16x16x32_bf16 v[56:59], v[56:59], v[92:95], 0
	s_waitcnt lgkmcnt(0)
	v_mfma_f32_16x16x32_bf16 v[108:111], v[60:63], v[88:91], v[64:67]
	v_mfma_f32_16x16x32_bf16 v[56:59], v[60:63], v[96:99], v[56:59]
	ds_read_b128 v[60:63], v153 offset:6912
	s_nop 2
	ds_read_b128 v[64:67], v153 offset:6976
	s_waitcnt lgkmcnt(1)
	v_mfma_f32_16x16x32_bf16 v[68:71], v[60:63], v[84:87], 0
	v_mfma_f32_16x16x32_bf16 v[60:63], v[60:63], v[92:95], 0
	s_waitcnt lgkmcnt(0)
	v_mfma_f32_16x16x32_bf16 v[112:115], v[64:67], v[88:91], v[68:71]
	v_mfma_f32_16x16x32_bf16 v[60:63], v[64:67], v[96:99], v[60:63]
	ds_read_b128 v[64:67], v153 offset:9216
	s_nop 2
	ds_read_b128 v[68:71], v153 offset:9280
	s_waitcnt lgkmcnt(1)
	v_mfma_f32_16x16x32_bf16 v[72:75], v[64:67], v[84:87], 0
	v_mfma_f32_16x16x32_bf16 v[64:67], v[64:67], v[92:95], 0
	s_waitcnt lgkmcnt(0)
	v_mfma_f32_16x16x32_bf16 v[116:119], v[68:71], v[88:91], v[72:75]
	v_mfma_f32_16x16x32_bf16 v[64:67], v[68:71], v[96:99], v[64:67]
	ds_read_b128 v[68:71], v153 offset:11520
	s_nop 2
	ds_read_b128 v[72:75], v153 offset:11584
	s_waitcnt lgkmcnt(1)
	v_mfma_f32_16x16x32_bf16 v[76:79], v[68:71], v[84:87], 0
	v_mfma_f32_16x16x32_bf16 v[68:71], v[68:71], v[92:95], 0
	s_waitcnt lgkmcnt(0)
	v_mfma_f32_16x16x32_bf16 v[120:123], v[72:75], v[88:91], v[76:79]
	v_mfma_f32_16x16x32_bf16 v[68:71], v[72:75], v[96:99], v[68:71]
	ds_read_b128 v[72:75], v153 offset:13824
	s_nop 2
	ds_read_b128 v[76:79], v153 offset:13888
	s_waitcnt lgkmcnt(1)
	v_mfma_f32_16x16x32_bf16 v[80:83], v[72:75], v[84:87], 0
	v_mfma_f32_16x16x32_bf16 v[72:75], v[72:75], v[92:95], 0
	s_waitcnt lgkmcnt(0)
	v_mfma_f32_16x16x32_bf16 v[124:127], v[76:79], v[88:91], v[80:83]
	v_mfma_f32_16x16x32_bf16 v[72:75], v[76:79], v[96:99], v[72:75]
	ds_read_b128 v[76:79], v153 offset:16128
	s_nop 2
	ds_read_b128 v[80:83], v153 offset:16192
	s_waitcnt lgkmcnt(1)
	v_mfma_f32_16x16x32_bf16 v[164:167], v[76:79], v[84:87], 0
	v_mfma_f32_16x16x32_bf16 v[76:79], v[76:79], v[92:95], 0
	s_waitcnt lgkmcnt(0)
	v_mfma_f32_16x16x32_bf16 v[164:167], v[80:83], v[88:91], v[164:167]
	v_mfma_f32_16x16x32_bf16 v[76:79], v[80:83], v[96:99], v[76:79]
	ds_read_b128 v[80:83], v153 offset:18432
	ds_read_b128 v[168:171], v153 offset:18496
	s_waitcnt lgkmcnt(1)
	v_mfma_f32_16x16x32_bf16 v[172:175], v[80:83], v[84:87], 0
	v_mfma_f32_16x16x32_bf16 v[80:83], v[80:83], v[92:95], 0
	s_waitcnt lgkmcnt(0)
	v_mfma_f32_16x16x32_bf16 v[210:213], v[168:171], v[88:91], v[172:175]
	v_mfma_f32_16x16x32_bf16 v[80:83], v[168:171], v[96:99], v[80:83]
	ds_read_b128 v[168:171], v153 offset:20736
	s_nop 2
	ds_read_b128 v[172:175], v153 offset:20800
	s_waitcnt lgkmcnt(1)
	v_mfma_f32_16x16x32_bf16 v[84:87], v[168:171], v[84:87], 0
	s_waitcnt lgkmcnt(0)
	v_mfma_f32_16x16x32_bf16 v[214:217], v[172:175], v[88:91], v[84:87]
	v_mfma_f32_16x16x32_bf16 v[84:87], v[168:171], v[92:95], 0
	v_mov_b32_e32 v92, 0xf149f2ca
	v_cndmask_b32_e32 v92, 0, v92, vcc
	v_mfma_f32_16x16x32_bf16 v[84:87], v[172:175], v[96:99], v[84:87]
	ds_read2_b32 v[94:95], v139 offset0:159 offset1:160
	ds_read2_b32 v[96:97], v139 offset0:157 offset1:158
	ds_read2_b32 v[98:99], v139 offset0:143 offset1:144
	ds_read2_b32 v[176:177], v139 offset0:141 offset1:142
	ds_read2_b32 v[178:179], v139 offset0:127 offset1:128
	ds_read2_b32 v[180:181], v139 offset0:125 offset1:126
	ds_read2_b32 v[182:183], v139 offset0:111 offset1:112
	ds_read2_b32 v[184:185], v139 offset0:109 offset1:110
	ds_read2_b32 v[186:187], v139 offset0:95 offset1:96
	ds_read2_b32 v[188:189], v139 offset0:93 offset1:94
	ds_read2_b32 v[190:191], v139 offset0:79 offset1:80
	ds_read2_b32 v[192:193], v139 offset0:77 offset1:78
	ds_read2_b32 v[194:195], v139 offset0:63 offset1:64
	ds_read2_b32 v[196:197], v139 offset0:61 offset1:62
	ds_read2_b32 v[90:91], v139 offset0:47 offset1:48
	ds_read2_b32 v[88:89], v139 offset0:45 offset1:46
	ds_read2_b32 v[198:199], v139 offset0:31 offset1:32
	ds_read2_b32 v[218:219], v139 offset0:29 offset1:30
	ds_read2_b32 v[220:221], v139 offset0:15 offset1:16
	ds_read2_b32 v[222:223], v139 offset0:13 offset1:14
	s_waitcnt lgkmcnt(14)
	v_add_f32_e32 v169, v92, v95
	v_add_f32_e32 v170, v92, v94
	v_add_f32_e32 v93, v100, v169
	v_add_f32_e32 v94, v101, v170
	v_add_f32_e32 v171, v92, v97
	v_add_f32_e32 v172, v92, v96
	v_max3_f32 v95, v93, s7, v94
	v_add_f32_e32 v97, v102, v171
	v_add_f32_e32 v96, v103, v172
	v_add_f32_e32 v173, v92, v99
	v_add_f32_e32 v174, v92, v98
	v_max3_f32 v95, v95, v97, v96
	v_add_f32_e32 v99, v104, v173
	v_add_f32_e32 v98, v105, v174
	v_add_f32_e32 v175, v92, v177
	v_add_f32_e32 v176, v92, v176
	v_max3_f32 v95, v95, v99, v98
	v_add_f32_e32 v100, v106, v175
	v_add_f32_e32 v101, v107, v176
	v_add_f32_e32 v177, v92, v179
	v_add_f32_e32 v178, v92, v178
	v_max3_f32 v95, v95, v100, v101
	v_add_f32_e32 v102, v108, v177
	v_add_f32_e32 v103, v109, v178
	v_add_f32_e32 v179, v92, v181
	v_add_f32_e32 v180, v92, v180
	v_max3_f32 v95, v95, v102, v103
	v_add_f32_e32 v104, v110, v179
	v_add_f32_e32 v105, v111, v180
	s_waitcnt lgkmcnt(13)
	v_add_f32_e32 v181, v92, v183
	v_add_f32_e32 v182, v92, v182
	v_max3_f32 v95, v95, v104, v105
	v_add_f32_e32 v106, v112, v181
	v_add_f32_e32 v107, v113, v182
	s_waitcnt lgkmcnt(12)
	v_add_f32_e32 v183, v92, v185
	v_add_f32_e32 v184, v92, v184
	v_max3_f32 v95, v95, v106, v107
	v_add_f32_e32 v108, v114, v183
	v_add_f32_e32 v109, v115, v184
	s_waitcnt lgkmcnt(11)
	v_add_f32_e32 v185, v92, v187
	v_add_f32_e32 v186, v92, v186
	v_max3_f32 v95, v95, v108, v109
	v_add_f32_e32 v110, v116, v185
	v_add_f32_e32 v111, v117, v186
	s_waitcnt lgkmcnt(10)
	v_add_f32_e32 v187, v92, v189
	v_add_f32_e32 v188, v92, v188
	v_max3_f32 v95, v95, v110, v111
	v_add_f32_e32 v112, v118, v187
	v_add_f32_e32 v113, v119, v188
	s_waitcnt lgkmcnt(9)
	v_add_f32_e32 v189, v92, v191
	v_add_f32_e32 v190, v92, v190
	v_max3_f32 v95, v95, v112, v113
	v_add_f32_e32 v114, v120, v189
	v_add_f32_e32 v115, v121, v190
	s_waitcnt lgkmcnt(8)
	v_add_f32_e32 v191, v92, v193
	v_add_f32_e32 v192, v92, v192
	v_max3_f32 v95, v95, v114, v115
	v_add_f32_e32 v116, v122, v191
	v_add_f32_e32 v117, v123, v192
	s_waitcnt lgkmcnt(7)
	v_add_f32_e32 v193, v92, v195
	v_add_f32_e32 v194, v92, v194
	s_waitcnt lgkmcnt(5)
	v_add_f32_e32 v118, v92, v91
	v_max3_f32 v95, v95, v116, v117
	v_add_f32_e32 v224, v124, v193
	v_add_f32_e32 v225, v125, v194
	v_add_f32_e32 v195, v92, v197
	v_add_f32_e32 v196, v92, v196
	v_add_f32_e32 v228, v164, v118
	v_add_f32_e32 v118, v92, v90
	v_max3_f32 v95, v95, v224, v225
	v_add_f32_e32 v226, v126, v195
	v_add_f32_e32 v227, v127, v196
	v_add_f32_e32 v229, v165, v118
	s_waitcnt lgkmcnt(4)
	v_add_f32_e32 v118, v92, v89
	v_max3_f32 v95, v95, v226, v227
	v_add_f32_e32 v230, v166, v118
	v_add_f32_e32 v118, v92, v88
	v_max3_f32 v95, v95, v228, v229
	v_add_f32_e32 v231, v167, v118
	s_waitcnt lgkmcnt(3)
	v_add_f32_e32 v197, 0, v199
	v_add_f32_e32 v198, 0, v198
	s_waitcnt lgkmcnt(1)
	v_add_f32_e32 v118, 0, v221
	v_max3_f32 v95, v95, v230, v231
	v_add_f32_e32 v232, v210, v197
	v_add_f32_e32 v211, v211, v198
	v_add_f32_e32 v199, 0, v219
	v_add_f32_e32 v210, 0, v218
	v_add_f32_e32 v214, v214, v118
	v_add_f32_e32 v118, 0, v220
	v_max3_f32 v95, v95, v232, v211
	v_add_f32_e32 v212, v212, v199
	v_add_f32_e32 v213, v213, v210
	v_add_f32_e32 v215, v215, v118
	s_waitcnt lgkmcnt(0)
	v_add_f32_e32 v118, 0, v223
	v_max3_f32 v95, v95, v212, v213
	v_add_f32_e32 v216, v216, v118
	v_add_f32_e32 v118, 0, v222
	v_max3_f32 v95, v95, v214, v215
	v_add_f32_e32 v217, v217, v118
	v_max3_f32 v95, v95, v216, v217
	ds_bpermute_b32 v118, v140, v95
	v_add_f32_e32 v52, v52, v169
	v_add_f32_e32 v53, v53, v170
	v_add_f32_e32 v54, v54, v171
	v_add_f32_e32 v55, v55, v172
	s_waitcnt lgkmcnt(0)
	v_max_f32_e32 v118, v118, v118
	v_max_f32_e32 v95, v95, v118
	ds_bpermute_b32 v118, v141, v95
	v_add_f32_e32 v56, v56, v173
	v_add_f32_e32 v57, v57, v174
	v_add_f32_e32 v58, v58, v175
	v_add_f32_e32 v59, v59, v176
	s_waitcnt lgkmcnt(0)
	v_max3_f32 v218, v95, v118, v133
	v_sub_f32_e32 v93, v93, v218
	v_exp_f32_e32 v126, v93
	v_sub_f32_e32 v94, v94, v218
	v_exp_f32_e32 v127, v94
	v_sub_f32_e32 v94, v97, v218
	v_exp_f32_e32 v163, v94
	v_sub_f32_e32 v94, v96, v218
	v_exp_f32_e32 v164, v94
	v_sub_f32_e32 v94, v99, v218
	v_add_f32_e32 v93, 0, v126
	v_exp_f32_e32 v165, v94
	v_sub_f32_e32 v94, v98, v218
	v_add_f32_e32 v93, v127, v93
	v_exp_f32_e32 v166, v94
	v_sub_f32_e32 v94, v100, v218
	v_add_f32_e32 v93, v163, v93
	v_exp_f32_e32 v167, v94
	v_sub_f32_e32 v94, v101, v218
	v_add_f32_e32 v93, v164, v93
	v_exp_f32_e32 v168, v94
	v_sub_f32_e32 v94, v102, v218
	v_add_f32_e32 v93, v165, v93
	v_exp_f32_e32 v118, v94
	v_sub_f32_e32 v94, v103, v218
	v_add_f32_e32 v93, v166, v93
	v_exp_f32_e32 v119, v94
	v_sub_f32_e32 v94, v104, v218
	v_add_f32_e32 v93, v167, v93
	v_exp_f32_e32 v120, v94
	v_sub_f32_e32 v94, v105, v218
	v_add_f32_e32 v93, v168, v93
	v_exp_f32_e32 v121, v94
	v_sub_f32_e32 v94, v106, v218
	v_add_f32_e32 v93, v118, v93
	v_exp_f32_e32 v122, v94
	v_sub_f32_e32 v94, v107, v218
	v_add_f32_e32 v93, v119, v93
	v_exp_f32_e32 v123, v94
	v_sub_f32_e32 v94, v108, v218
	v_add_f32_e32 v93, v120, v93
	v_exp_f32_e32 v124, v94
	v_sub_f32_e32 v94, v109, v218
	v_add_f32_e32 v93, v121, v93
	v_exp_f32_e32 v125, v94
	v_sub_f32_e32 v94, v110, v218
	v_add_f32_e32 v93, v122, v93
	v_exp_f32_e32 v110, v94
	v_sub_f32_e32 v94, v111, v218
	v_add_f32_e32 v93, v123, v93
	v_exp_f32_e32 v111, v94
	v_sub_f32_e32 v94, v112, v218
	v_add_f32_e32 v93, v124, v93
	v_exp_f32_e32 v112, v94
	v_sub_f32_e32 v94, v113, v218
	v_add_f32_e32 v93, v125, v93
	v_exp_f32_e32 v113, v94
	v_sub_f32_e32 v94, v114, v218
	v_add_f32_e32 v93, v110, v93
	v_exp_f32_e32 v114, v94
	v_sub_f32_e32 v94, v115, v218
	v_add_f32_e32 v93, v111, v93
	v_exp_f32_e32 v115, v94
	v_sub_f32_e32 v94, v116, v218
	v_add_f32_e32 v93, v112, v93
	v_exp_f32_e32 v116, v94
	v_sub_f32_e32 v94, v117, v218
	v_add_f32_e32 v93, v113, v93
	v_exp_f32_e32 v117, v94
	v_sub_f32_e32 v94, v224, v218
	v_add_f32_e32 v93, v114, v93
	v_exp_f32_e32 v102, v94
	v_sub_f32_e32 v94, v225, v218
	v_add_f32_e32 v93, v115, v93
	v_exp_f32_e32 v103, v94
	v_sub_f32_e32 v94, v226, v218
	v_add_f32_e32 v93, v116, v93
	v_exp_f32_e32 v104, v94
	v_sub_f32_e32 v94, v227, v218
	v_add_f32_e32 v93, v117, v93
	v_exp_f32_e32 v105, v94
	v_sub_f32_e32 v94, v228, v218
	v_add_f32_e32 v93, v102, v93
	v_exp_f32_e32 v106, v94
	v_sub_f32_e32 v94, v229, v218
	v_add_f32_e32 v93, v103, v93
	v_exp_f32_e32 v107, v94
	v_sub_f32_e32 v94, v230, v218
	v_add_f32_e32 v93, v104, v93
	v_exp_f32_e32 v108, v94
	v_sub_f32_e32 v94, v231, v218
	v_add_f32_e32 v93, v105, v93
	v_exp_f32_e32 v109, v94
	v_sub_f32_e32 v94, v232, v218
	v_add_f32_e32 v93, v106, v93
	v_exp_f32_e32 v94, v94
	v_sub_f32_e32 v95, v211, v218
	v_add_f32_e32 v93, v107, v93
	v_exp_f32_e32 v95, v95
	v_sub_f32_e32 v96, v212, v218
	v_add_f32_e32 v93, v108, v93
	v_exp_f32_e32 v96, v96
	v_sub_f32_e32 v97, v213, v218
	v_add_f32_e32 v93, v109, v93
	v_exp_f32_e32 v97, v97
	v_sub_f32_e32 v98, v214, v218
	v_add_f32_e32 v93, v94, v93
	v_exp_f32_e32 v98, v98
	v_sub_f32_e32 v99, v215, v218
	v_add_f32_e32 v93, v95, v93
	v_exp_f32_e32 v99, v99
	v_sub_f32_e32 v100, v216, v218
	v_add_f32_e32 v93, v96, v93
	v_exp_f32_e32 v100, v100
	v_sub_f32_e32 v101, v217, v218
	v_add_f32_e32 v93, v97, v93
	v_exp_f32_e32 v101, v101
	v_add_f32_e32 v93, v98, v93
	v_add_f32_e32 v93, v99, v93
	v_add_f32_e32 v93, v100, v93
	v_add_f32_e32 v93, v101, v93
	ds_bpermute_b32 v211, v140, v93
	v_add_f32_e32 v60, v60, v177
	v_add_f32_e32 v61, v61, v178
	v_add_f32_e32 v62, v62, v179
	v_add_f32_e32 v63, v63, v180
	s_waitcnt lgkmcnt(0)
	v_add_f32_e32 v93, v93, v211
	ds_bpermute_b32 v211, v141, v93
	v_add_f32_e32 v64, v64, v181
	v_add_f32_e32 v170, v65, v182
	v_add_f32_e32 v171, v67, v184
	v_add_f32_e32 v172, v68, v185
	s_waitcnt lgkmcnt(0)
	v_add_f32_e32 v93, v93, v211
	v_fma_f32 v211, v162, s6, -v218
	v_exp_f32_e32 v211, v211
	v_add_f32_e32 v173, v69, v186
	v_add_f32_e32 v174, v70, v187
	v_add_f32_e32 v175, v71, v188
	v_add_f32_e32 v93, v211, v93
	v_div_scale_f32 v211, s[0:1], v93, v93, 1.0
	v_rcp_f32_e32 v212, v211
	v_add_f32_e32 v176, v72, v189
	v_add_f32_e32 v177, v73, v190
	v_add_f32_e32 v178, v74, v191
	v_fma_f32 v213, -v211, v212, 1.0
	v_fmac_f32_e32 v212, v213, v212
	v_div_scale_f32 v213, vcc, 1.0, v93, 1.0
	v_mul_f32_e32 v214, v213, v212
	v_fma_f32 v215, -v211, v214, v213
	v_fmac_f32_e32 v214, v215, v212
	v_fma_f32 v211, -v211, v214, v213
	v_div_fmas_f32 v211, v211, v212, v214
	ds_read2_b32 v[212:213], v139 offset0:175 offset1:176
	ds_read2_b32 v[214:215], v139 offset0:173 offset1:174
	v_div_fixup_f32 v93, v211, v93, 1.0
	v_add_f32_e32 v179, v75, v192
	v_add_f32_e32 v180, v76, v193
	s_waitcnt lgkmcnt(1)
	v_add_f32_e32 v211, v92, v213
	v_add_f32_e32 v48, v48, v211
	v_add_f32_e32 v211, v92, v212
	s_waitcnt lgkmcnt(0)
	v_add_f32_e32 v212, v92, v215
	v_add_f32_e32 v49, v49, v211
	v_add_f32_e32 v50, v50, v212
	v_add_f32_e32 v212, v92, v214
	v_max3_f32 v211, v48, s7, v49
	v_add_f32_e32 v51, v51, v212
	v_max3_f32 v211, v211, v50, v51
	v_max3_f32 v169, v211, v52, v53
	v_max3_f32 v169, v169, v54, v55
	v_max3_f32 v169, v169, v56, v57
	v_max3_f32 v169, v169, v58, v59
	v_max3_f32 v169, v169, v60, v61
	v_max3_f32 v169, v169, v62, v63
	v_max3_f32 v65, v169, v64, v170
	v_add_f32_e32 v169, v66, v183
	v_max3_f32 v65, v65, v169, v171
	v_max3_f32 v65, v65, v172, v173
	v_max3_f32 v65, v65, v174, v175
	v_max3_f32 v65, v65, v176, v177
	v_add_f32_e32 v66, 0, v91
	v_max3_f32 v65, v65, v178, v179
	v_add_f32_e32 v181, v77, v194
	v_add_f32_e32 v91, v80, v66
	v_add_f32_e32 v66, 0, v90
	v_max3_f32 v65, v65, v180, v181
	v_add_f32_e32 v182, v78, v195
	v_add_f32_e32 v183, v79, v196
	v_add_f32_e32 v90, v81, v66
	v_add_f32_e32 v66, 0, v89
	v_max3_f32 v65, v65, v182, v183
	v_add_f32_e32 v89, v82, v66
	v_add_f32_e32 v66, 0, v88
	v_max3_f32 v65, v65, v91, v90
	v_add_f32_e32 v184, v83, v66
	v_max3_f32 v65, v65, v89, v184
	v_add_f32_e32 v185, v84, v197
	v_add_f32_e32 v186, v85, v198
	v_max3_f32 v65, v65, v185, v186
	v_add_f32_e32 v187, v86, v199
	v_add_f32_e32 v188, v87, v210
	v_max3_f32 v65, v65, v187, v188
	ds_bpermute_b32 v66, v140, v65
	s_waitcnt lgkmcnt(0)
	v_max_f32_e32 v66, v66, v66
	v_max_f32_e32 v65, v65, v66
	ds_bpermute_b32 v66, v141, v65
	s_waitcnt lgkmcnt(0)
	v_max3_f32 v189, v65, v66, v133
	v_sub_f32_e32 v48, v48, v189
	v_exp_f32_e32 v81, v48
	v_sub_f32_e32 v49, v49, v189
	v_exp_f32_e32 v82, v49
	v_sub_f32_e32 v49, v50, v189
	v_exp_f32_e32 v83, v49
	v_sub_f32_e32 v49, v51, v189
	v_exp_f32_e32 v84, v49
	v_sub_f32_e32 v49, v52, v189
	v_add_f32_e32 v48, 0, v81
	v_exp_f32_e32 v85, v49
	v_sub_f32_e32 v49, v53, v189
	v_add_f32_e32 v48, v82, v48
	v_exp_f32_e32 v86, v49
	v_sub_f32_e32 v49, v54, v189
	v_add_f32_e32 v48, v83, v48
	v_exp_f32_e32 v87, v49
	v_sub_f32_e32 v49, v55, v189
	v_add_f32_e32 v48, v84, v48
	v_exp_f32_e32 v88, v49
	v_sub_f32_e32 v49, v56, v189
	v_add_f32_e32 v48, v85, v48
	v_exp_f32_e32 v73, v49
	v_sub_f32_e32 v49, v57, v189
	v_add_f32_e32 v48, v86, v48
	v_exp_f32_e32 v74, v49
	v_sub_f32_e32 v49, v58, v189
	v_add_f32_e32 v48, v87, v48
	v_exp_f32_e32 v75, v49
	v_sub_f32_e32 v49, v59, v189
	v_add_f32_e32 v48, v88, v48
	v_exp_f32_e32 v76, v49
	v_sub_f32_e32 v49, v60, v189
	v_add_f32_e32 v48, v73, v48
	v_exp_f32_e32 v77, v49
	v_sub_f32_e32 v49, v61, v189
	v_add_f32_e32 v48, v74, v48
	v_exp_f32_e32 v78, v49
	v_sub_f32_e32 v49, v62, v189
	v_add_f32_e32 v48, v75, v48
	v_exp_f32_e32 v79, v49
	v_sub_f32_e32 v49, v63, v189
	v_add_f32_e32 v48, v76, v48
	v_exp_f32_e32 v80, v49
	v_sub_f32_e32 v49, v64, v189
	v_add_f32_e32 v48, v77, v48
	v_exp_f32_e32 v65, v49
	v_sub_f32_e32 v49, v170, v189
	v_add_f32_e32 v48, v78, v48
	v_exp_f32_e32 v66, v49
	v_sub_f32_e32 v49, v169, v189
	v_add_f32_e32 v48, v79, v48
	v_exp_f32_e32 v67, v49
	v_sub_f32_e32 v49, v171, v189
	v_add_f32_e32 v48, v80, v48
	v_exp_f32_e32 v68, v49
	v_sub_f32_e32 v49, v172, v189
	v_add_f32_e32 v48, v65, v48
	v_exp_f32_e32 v69, v49
	v_sub_f32_e32 v49, v173, v189
	v_add_f32_e32 v48, v66, v48
	v_exp_f32_e32 v70, v49
	v_sub_f32_e32 v49, v174, v189
	v_add_f32_e32 v48, v67, v48
	v_exp_f32_e32 v71, v49
	v_sub_f32_e32 v49, v175, v189
	v_add_f32_e32 v48, v68, v48
	v_exp_f32_e32 v72, v49
	v_sub_f32_e32 v49, v176, v189
	v_add_f32_e32 v48, v69, v48
	v_exp_f32_e32 v57, v49
	v_sub_f32_e32 v49, v177, v189
	v_add_f32_e32 v48, v70, v48
	v_exp_f32_e32 v58, v49
	v_sub_f32_e32 v49, v178, v189
	v_add_f32_e32 v48, v71, v48
	v_exp_f32_e32 v59, v49
	v_sub_f32_e32 v49, v179, v189
	v_add_f32_e32 v48, v72, v48
	v_exp_f32_e32 v60, v49
	v_sub_f32_e32 v49, v180, v189
	v_add_f32_e32 v48, v57, v48
	v_exp_f32_e32 v61, v49
	v_sub_f32_e32 v49, v181, v189
	v_add_f32_e32 v48, v58, v48
	v_exp_f32_e32 v62, v49
	v_sub_f32_e32 v49, v182, v189
	v_add_f32_e32 v48, v59, v48
	v_exp_f32_e32 v63, v49
	v_sub_f32_e32 v49, v183, v189
	v_add_f32_e32 v48, v60, v48
	v_exp_f32_e32 v64, v49
	v_sub_f32_e32 v49, v91, v189
	v_add_f32_e32 v48, v61, v48
	v_exp_f32_e32 v49, v49
	v_sub_f32_e32 v50, v90, v189
	v_add_f32_e32 v48, v62, v48
	v_exp_f32_e32 v50, v50
	v_sub_f32_e32 v51, v89, v189
	v_add_f32_e32 v48, v63, v48
	v_exp_f32_e32 v51, v51
	v_sub_f32_e32 v52, v184, v189
	v_add_f32_e32 v48, v64, v48
	v_exp_f32_e32 v52, v52
	v_sub_f32_e32 v53, v185, v189
	v_add_f32_e32 v48, v49, v48
	v_exp_f32_e32 v53, v53
	v_sub_f32_e32 v54, v186, v189
	v_add_f32_e32 v48, v50, v48
	v_exp_f32_e32 v54, v54
	v_sub_f32_e32 v55, v187, v189
	v_add_f32_e32 v48, v51, v48
	v_exp_f32_e32 v55, v55
	v_sub_f32_e32 v56, v188, v189
	v_add_f32_e32 v48, v52, v48
	v_exp_f32_e32 v56, v56
	v_add_f32_e32 v48, v53, v48
	v_add_f32_e32 v48, v54, v48
	v_add_f32_e32 v48, v55, v48
	v_add_f32_e32 v48, v56, v48
	ds_bpermute_b32 v89, v140, v48
	s_waitcnt lgkmcnt(0)
	v_add_f32_e32 v48, v48, v89
	ds_bpermute_b32 v89, v141, v48
	s_waitcnt lgkmcnt(0)
	v_add_f32_e32 v48, v48, v89
	v_fma_f32 v89, v162, s6, -v189
	v_exp_f32_e32 v89, v89
	s_nop 0
	v_add_f32_e32 v48, v89, v48
	v_div_scale_f32 v89, s[0:1], v48, v48, 1.0
	v_rcp_f32_e32 v90, v89
	s_nop 0
	v_fma_f32 v91, -v89, v90, 1.0
	v_fmac_f32_e32 v90, v91, v90
	v_div_scale_f32 v91, vcc, 1.0, v48, 1.0
	v_mul_f32_e32 v169, v91, v90
	v_fma_f32 v170, -v89, v169, v91
	v_fmac_f32_e32 v169, v170, v90
	v_fma_f32 v89, -v89, v169, v91
	v_div_fmas_f32 v89, v89, v90, v169
	v_div_fixup_f32 v48, v89, v48, 1.0
	v_cvt_pk_bf16_f32 v170, v126, v127
	v_cvt_pk_bf16_f32 v171, v163, v164
	v_cvt_pk_bf16_f32 v172, v165, v166
	v_cvt_pk_bf16_f32 v173, v167, v168
	v_cvt_pk_bf16_f32 v82, v81, v82
	v_cvt_pk_bf16_f32 v83, v83, v84
	v_cvt_pk_bf16_f32 v84, v85, v86
	v_cvt_pk_bf16_f32 v85, v87, v88
	ds_read_b128 v[86:89], v142 offset:36864
	ds_read_b128 v[174:177], v142 offset:45312
	ds_read_b128 v[182:185], v142 offset:53760
	ds_read_b128 v[190:193], v142 offset:62208
	v_cvt_pk_bf16_f32 v118, v118, v119
	v_cvt_pk_bf16_f32 v119, v120, v121
	v_cvt_pk_bf16_f32 v120, v122, v123
	v_cvt_pk_bf16_f32 v121, v124, v125
	v_cvt_pk_bf16_f32 v74, v73, v74
	v_cvt_pk_bf16_f32 v75, v75, v76
	v_cvt_pk_bf16_f32 v76, v77, v78
	v_cvt_pk_bf16_f32 v77, v79, v80
	ds_read_b128 v[78:81], v142 offset:36928
	s_waitcnt lgkmcnt(4)
	v_mfma_f32_16x16x32_bf16 v[164:167], v[86:89], v[170:173], 0
	v_mfma_f32_16x16x32_bf16 v[86:89], v[86:89], v[82:85], 0
	s_waitcnt lgkmcnt(0)
	v_mfma_f32_16x16x32_bf16 v[122:125], v[78:81], v[118:121], v[164:167]
	v_mfma_f32_16x16x32_bf16 v[78:81], v[78:81], v[74:77], v[86:89]
	s_nop 4
	ds_read_b128 v[86:89], v142 offset:45376
	v_mfma_f32_16x16x32_bf16 v[178:181], v[174:177], v[170:173], 0
	v_mfma_f32_16x16x32_bf16 v[174:177], v[174:177], v[82:85], 0
	v_mfma_f32_16x16x32_bf16 v[186:189], v[182:185], v[170:173], 0
	v_mfma_f32_16x16x32_bf16 v[168:171], v[190:193], v[170:173], 0
	s_waitcnt lgkmcnt(0)
	v_mfma_f32_16x16x32_bf16 v[164:167], v[86:89], v[118:121], v[178:181]
	v_mfma_f32_16x16x32_bf16 v[86:89], v[86:89], v[74:77], v[174:177]
	s_nop 2
	ds_read_b128 v[172:175], v142 offset:53824
	v_mfma_f32_16x16x32_bf16 v[182:185], v[182:185], v[82:85], 0
	s_waitcnt lgkmcnt(0)
	v_mfma_f32_16x16x32_bf16 v[176:179], v[172:175], v[118:121], v[186:189]
	v_mfma_f32_16x16x32_bf16 v[172:175], v[172:175], v[74:77], v[182:185]
	s_nop 4
	ds_read_b128 v[180:183], v142 offset:62272
	v_mfma_f32_16x16x32_bf16 v[82:85], v[190:193], v[82:85], 0
	s_waitcnt lgkmcnt(0)
	v_mfma_f32_16x16x32_bf16 v[74:77], v[180:183], v[74:77], v[82:85]
	v_cvt_pk_bf16_f32 v82, v110, v111
	v_cvt_pk_bf16_f32 v83, v112, v113
	v_cvt_pk_bf16_f32 v84, v114, v115
	v_cvt_pk_bf16_f32 v85, v116, v117
	v_cvt_pk_bf16_f32 v66, v65, v66
	v_cvt_pk_bf16_f32 v67, v67, v68
	v_cvt_pk_bf16_f32 v68, v69, v70
	v_cvt_pk_bf16_f32 v69, v71, v72
	ds_read_b128 v[70:73], v142 offset:36992
	s_waitcnt lgkmcnt(0)
	s_nop 3
	v_mfma_f32_16x16x32_bf16 v[110:113], v[70:73], v[82:85], v[122:125]
	v_mfma_f32_16x16x32_bf16 v[70:73], v[70:73], v[66:69], v[78:81]
	s_nop 2
	ds_read_b128 v[78:81], v142 offset:45440
	s_waitcnt lgkmcnt(0)
	v_mfma_f32_16x16x32_bf16 v[114:117], v[78:81], v[82:85], v[164:167]
	s_nop 2
	ds_read_b128 v[164:167], v142 offset:62336
	v_mfma_f32_16x16x32_bf16 v[78:81], v[78:81], v[66:69], v[86:89]
	s_nop 2
	ds_read_b128 v[86:89], v142 offset:53888
	s_waitcnt lgkmcnt(0)
	v_mfma_f32_16x16x32_bf16 v[122:125], v[86:89], v[82:85], v[176:179]
	v_mfma_f32_16x16x32_bf16 v[86:89], v[86:89], v[66:69], v[172:175]
	v_mfma_f32_16x16x32_bf16 v[66:69], v[164:167], v[66:69], v[74:77]
	v_cvt_pk_bf16_f32 v74, v102, v103
	v_cvt_pk_bf16_f32 v75, v104, v105
	v_cvt_pk_bf16_f32 v76, v106, v107
	v_cvt_pk_bf16_f32 v77, v108, v109
	v_cvt_pk_bf16_f32 v58, v57, v58
	v_cvt_pk_bf16_f32 v59, v59, v60
	v_cvt_pk_bf16_f32 v60, v61, v62
	v_cvt_pk_bf16_f32 v61, v63, v64
	ds_read_b128 v[62:65], v142 offset:37056
	s_waitcnt lgkmcnt(0)
	v_mfma_f32_16x16x32_bf16 v[102:105], v[62:65], v[74:77], v[110:113]
	v_mfma_f32_16x16x32_bf16 v[62:65], v[62:65], v[58:61], v[70:73]
	s_nop 2
	ds_read_b128 v[70:73], v142 offset:45504
	s_waitcnt lgkmcnt(0)
	v_mfma_f32_16x16x32_bf16 v[106:109], v[70:73], v[74:77], v[114:117]
	v_mfma_f32_16x16x32_bf16 v[70:73], v[70:73], v[58:61], v[78:81]
	s_nop 2
	ds_read_b128 v[78:81], v142 offset:53952
	s_waitcnt lgkmcnt(0)
	v_mfma_f32_16x16x32_bf16 v[110:113], v[78:81], v[74:77], v[122:125]
	v_mfma_f32_16x16x32_bf16 v[78:81], v[78:81], v[58:61], v[86:89]
	s_nop 2
	ds_read_b128 v[86:89], v142 offset:62400
	s_waitcnt lgkmcnt(0)
	v_mfma_f32_16x16x32_bf16 v[58:61], v[86:89], v[58:61], v[66:69]
	v_cvt_pk_bf16_f32 v66, v94, v95
	v_cvt_pk_bf16_f32 v67, v96, v97
	v_cvt_pk_bf16_f32 v68, v98, v99
	v_cvt_pk_bf16_f32 v69, v100, v101
	v_cvt_pk_bf16_f32 v50, v49, v50
	v_cvt_pk_bf16_f32 v51, v51, v52
	v_cvt_pk_bf16_f32 v52, v53, v54
	v_cvt_pk_bf16_f32 v53, v55, v56
	ds_read_b128 v[54:57], v142 offset:37120
	v_mfma_f32_16x16x32_bf16 v[118:121], v[180:183], v[118:121], v[168:171]
	v_mfma_f32_16x16x32_bf16 v[82:85], v[164:167], v[82:85], v[118:121]
	v_mfma_f32_16x16x32_bf16 v[74:77], v[86:89], v[74:77], v[82:85]
	s_waitcnt lgkmcnt(0)
	v_mfma_f32_16x16x32_bf16 v[82:85], v[54:57], v[66:69], v[102:105]
	v_mfma_f32_16x16x32_bf16 v[54:57], v[54:57], v[50:53], v[62:65]
	s_nop 2
	ds_read_b128 v[62:65], v142 offset:45568
	s_waitcnt lgkmcnt(0)
	v_mfma_f32_16x16x32_bf16 v[86:89], v[62:65], v[66:69], v[106:109]
	s_nop 0
	v_mfma_f32_16x16x32_bf16 v[62:65], v[62:65], v[50:53], v[70:73]
	s_nop 2
	ds_read_b128 v[70:73], v142 offset:54016
	s_waitcnt lgkmcnt(0)
	v_mfma_f32_16x16x32_bf16 v[94:97], v[70:73], v[66:69], v[110:113]
	v_mfma_f32_16x16x32_bf16 v[70:73], v[70:73], v[50:53], v[78:81]
	s_nop 2
	ds_read_b128 v[78:81], v142 offset:62464
	s_waitcnt lgkmcnt(0)
	v_mfma_f32_16x16x32_bf16 v[50:53], v[78:81], v[50:53], v[58:61]
	s_nop 2
	v_lshl_add_u64 v[58:59], v[134:135], 0, v[136:137]
	v_mfma_f32_16x16x32_bf16 v[66:69], v[78:81], v[66:69], v[74:77]
	v_mul_f32_e32 v82, v93, v82
	v_mul_f32_e32 v83, v93, v83
	v_mul_f32_e32 v84, v93, v84
	v_mul_f32_e32 v85, v93, v85
	v_mul_f32_e32 v86, v93, v86
	v_mul_f32_e32 v87, v93, v87
	v_mul_f32_e32 v88, v93, v88
	v_mul_f32_e32 v89, v93, v89
	v_mul_f32_e32 v94, v93, v94
	v_mul_f32_e32 v95, v93, v95
	v_mul_f32_e32 v96, v93, v96
	v_mul_f32_e32 v97, v93, v97
	v_mul_f32_e32 v66, v93, v66
	v_mul_f32_e32 v67, v93, v67
	v_mul_f32_e32 v68, v93, v68
	v_mul_f32_e32 v69, v93, v69
	v_cvt_pk_bf16_f32 v82, v82, v83
	v_cvt_pk_bf16_f32 v83, v84, v85
	v_cvt_pk_bf16_f32 v84, v86, v87
	v_cvt_pk_bf16_f32 v85, v88, v89
	v_cvt_pk_bf16_f32 v94, v94, v95
	v_cvt_pk_bf16_f32 v95, v96, v97
	v_cvt_pk_bf16_f32 v96, v66, v67
	v_cvt_pk_bf16_f32 v97, v68, v69
	s_nop 1
	v_permlane16_swap_b32_e32 v82, v84
	v_permlane16_swap_b32_e32 v83, v85
	v_permlane16_swap_b32_e32 v94, v96
	v_permlane16_swap_b32_e32 v95, v97
	global_store_dwordx4 v[58:59], v[82:85], off
	global_store_dwordx4 v[58:59], v[94:97], off offset:64
	v_or_b32_e32 v58, 16, v132
	v_ashrrev_i32_e32 v59, 31, v58
	v_lshlrev_b64 v[58:59], 12, v[58:59]
	v_lshl_add_u64 v[58:59], v[134:135], 0, v[58:59]
	v_mul_f32_e32 v54, v48, v54
	v_mul_f32_e32 v55, v48, v55
	v_mul_f32_e32 v56, v48, v56
	v_mul_f32_e32 v57, v48, v57
	v_mul_f32_e32 v62, v48, v62
	v_mul_f32_e32 v63, v48, v63
	v_mul_f32_e32 v64, v48, v64
	v_mul_f32_e32 v65, v48, v65
	v_mul_f32_e32 v70, v48, v70
	v_mul_f32_e32 v71, v48, v71
	v_mul_f32_e32 v72, v48, v72
	v_mul_f32_e32 v73, v48, v73
	v_mul_f32_e32 v50, v48, v50
	v_mul_f32_e32 v51, v48, v51
	v_mul_f32_e32 v52, v48, v52
	v_mul_f32_e32 v53, v48, v53
	v_cvt_pk_bf16_f32 v54, v54, v55
	v_cvt_pk_bf16_f32 v55, v56, v57
	v_cvt_pk_bf16_f32 v56, v62, v63
	v_cvt_pk_bf16_f32 v57, v64, v65
	v_cvt_pk_bf16_f32 v70, v70, v71
	v_cvt_pk_bf16_f32 v71, v72, v73
	v_cvt_pk_bf16_f32 v72, v50, v51
	v_cvt_pk_bf16_f32 v73, v52, v53
	s_nop 1
	v_permlane16_swap_b32_e32 v54, v56
	v_permlane16_swap_b32_e32 v55, v57
	v_permlane16_swap_b32_e32 v70, v72
	v_permlane16_swap_b32_e32 v71, v73
	global_store_dwordx4 v[58:59], v[54:57], off
	global_store_dwordx4 v[58:59], v[70:73], off offset:64
	ds_read_b128 v[48:51], v153 offset:4608
	ds_read_b128 v[52:55], v153 offset:4672
	s_waitcnt vmcnt(15) lgkmcnt(1)
	v_mfma_f32_16x16x32_bf16 v[56:59], v[48:51], v[36:39], 0
	s_waitcnt vmcnt(13)
	v_mfma_f32_16x16x32_bf16 v[48:51], v[48:51], v[40:43], 0
	s_waitcnt lgkmcnt(0)
	v_mfma_f32_16x16x32_bf16 v[84:87], v[52:55], v[32:35], v[56:59]
	s_waitcnt vmcnt(12)
	v_mfma_f32_16x16x32_bf16 v[48:51], v[52:55], v[44:47], v[48:51]
	ds_read_b128 v[52:55], v153 offset:6912
	s_nop 0
	ds_read_b128 v[56:59], v153 offset:6976
	s_waitcnt lgkmcnt(1)
	v_mfma_f32_16x16x32_bf16 v[60:63], v[52:55], v[36:39], 0
	v_mfma_f32_16x16x32_bf16 v[52:55], v[52:55], v[40:43], 0
	s_waitcnt lgkmcnt(0)
	v_mfma_f32_16x16x32_bf16 v[88:91], v[56:59], v[32:35], v[60:63]
	v_mfma_f32_16x16x32_bf16 v[52:55], v[56:59], v[44:47], v[52:55]
	ds_read_b128 v[56:59], v153 offset:9216
	s_nop 2
	ds_read_b128 v[60:63], v153 offset:9280
	s_waitcnt lgkmcnt(1)
	v_mfma_f32_16x16x32_bf16 v[64:67], v[56:59], v[36:39], 0
	v_mfma_f32_16x16x32_bf16 v[56:59], v[56:59], v[40:43], 0
	s_waitcnt lgkmcnt(0)
	v_mfma_f32_16x16x32_bf16 v[94:97], v[60:63], v[32:35], v[64:67]
	v_mfma_f32_16x16x32_bf16 v[56:59], v[60:63], v[44:47], v[56:59]
	ds_read_b128 v[60:63], v153 offset:11520
	s_nop 2
	ds_read_b128 v[64:67], v153 offset:11584
	s_waitcnt lgkmcnt(1)
	v_mfma_f32_16x16x32_bf16 v[68:71], v[60:63], v[36:39], 0
	v_mfma_f32_16x16x32_bf16 v[60:63], v[60:63], v[40:43], 0
	s_waitcnt lgkmcnt(0)
	v_mfma_f32_16x16x32_bf16 v[98:101], v[64:67], v[32:35], v[68:71]
	v_mfma_f32_16x16x32_bf16 v[60:63], v[64:67], v[44:47], v[60:63]
	ds_read_b128 v[64:67], v153 offset:13824
	s_nop 2
	ds_read_b128 v[68:71], v153 offset:13888
	s_waitcnt lgkmcnt(1)
	v_mfma_f32_16x16x32_bf16 v[72:75], v[64:67], v[36:39], 0
	v_mfma_f32_16x16x32_bf16 v[64:67], v[64:67], v[40:43], 0
	s_waitcnt lgkmcnt(0)
	v_mfma_f32_16x16x32_bf16 v[102:105], v[68:71], v[32:35], v[72:75]
	v_mfma_f32_16x16x32_bf16 v[64:67], v[68:71], v[44:47], v[64:67]
	ds_read_b128 v[68:71], v153 offset:16128
	s_nop 2
	ds_read_b128 v[72:75], v153 offset:16192
	s_waitcnt lgkmcnt(1)
	v_mfma_f32_16x16x32_bf16 v[76:79], v[68:71], v[36:39], 0
	v_mfma_f32_16x16x32_bf16 v[68:71], v[68:71], v[40:43], 0
	s_waitcnt lgkmcnt(0)
	v_mfma_f32_16x16x32_bf16 v[106:109], v[72:75], v[32:35], v[76:79]
	v_mfma_f32_16x16x32_bf16 v[68:71], v[72:75], v[44:47], v[68:71]
	ds_read_b128 v[72:75], v153 offset:18432
	s_nop 2
	ds_read_b128 v[76:79], v153 offset:18496
	s_waitcnt lgkmcnt(1)
	v_mfma_f32_16x16x32_bf16 v[80:83], v[72:75], v[36:39], 0
	v_mfma_f32_16x16x32_bf16 v[72:75], v[72:75], v[40:43], 0
	s_waitcnt lgkmcnt(0)
	v_mfma_f32_16x16x32_bf16 v[110:113], v[76:79], v[32:35], v[80:83]
	v_mfma_f32_16x16x32_bf16 v[72:75], v[76:79], v[44:47], v[72:75]
	ds_read_b128 v[76:79], v153 offset:20736
	s_nop 2
	ds_read_b128 v[80:83], v153 offset:20800
	s_waitcnt lgkmcnt(1)
	v_mfma_f32_16x16x32_bf16 v[114:117], v[76:79], v[36:39], 0
	v_mfma_f32_16x16x32_bf16 v[76:79], v[76:79], v[40:43], 0
	s_waitcnt lgkmcnt(0)
	v_mfma_f32_16x16x32_bf16 v[114:117], v[80:83], v[32:35], v[114:117]
	v_mfma_f32_16x16x32_bf16 v[76:79], v[80:83], v[44:47], v[76:79]
	ds_read_b128 v[80:83], v153 offset:23040
	ds_read_b128 v[118:121], v153 offset:23104
	s_waitcnt lgkmcnt(1)
	v_mfma_f32_16x16x32_bf16 v[122:125], v[80:83], v[36:39], 0
	v_mfma_f32_16x16x32_bf16 v[80:83], v[80:83], v[40:43], 0
	s_waitcnt lgkmcnt(0)
	v_mfma_f32_16x16x32_bf16 v[180:183], v[118:121], v[32:35], v[122:125]
	v_mfma_f32_16x16x32_bf16 v[80:83], v[118:121], v[44:47], v[80:83]
	ds_read_b128 v[118:121], v153 offset:25344
	s_nop 2
	ds_read_b128 v[122:125], v153 offset:25408
	s_waitcnt lgkmcnt(1)
	v_mfma_f32_16x16x32_bf16 v[36:39], v[118:121], v[36:39], 0
	s_waitcnt lgkmcnt(0)
	v_mfma_f32_16x16x32_bf16 v[184:187], v[122:125], v[32:35], v[36:39]
	v_mfma_f32_16x16x32_bf16 v[32:35], v[118:121], v[40:43], 0
	v_mfma_f32_16x16x32_bf16 v[32:35], v[122:125], v[44:47], v[32:35]
	ds_read2_b32 v[40:41], v139 offset0:159 offset1:160
	ds_read2_b32 v[42:43], v139 offset0:157 offset1:158
	ds_read2_b32 v[44:45], v139 offset0:143 offset1:144
	ds_read2_b32 v[46:47], v139 offset0:141 offset1:142
	ds_read2_b32 v[136:137], v139 offset0:127 offset1:128
	ds_read2_b32 v[164:165], v139 offset0:125 offset1:126
	ds_read2_b32 v[166:167], v139 offset0:111 offset1:112
	ds_read2_b32 v[168:169], v139 offset0:109 offset1:110
	ds_read2_b32 v[170:171], v139 offset0:95 offset1:96
	ds_read2_b32 v[172:173], v139 offset0:93 offset1:94
	ds_read2_b32 v[38:39], v139 offset0:79 offset1:80
	ds_read2_b32 v[36:37], v139 offset0:77 offset1:78
	ds_read2_b32 v[174:175], v139 offset0:63 offset1:64
	ds_read2_b32 v[176:177], v139 offset0:61 offset1:62
	ds_read2_b32 v[178:179], v139 offset0:47 offset1:48
	ds_read2_b32 v[188:189], v139 offset0:45 offset1:46
	ds_read2_b32 v[190:191], v139 offset0:31 offset1:32
	ds_read2_b32 v[192:193], v139 offset0:29 offset1:30
	ds_read2_b32 v[194:195], v139 offset0:15 offset1:16
	ds_read2_b32 v[196:197], v139 offset0:13 offset1:14
	s_waitcnt lgkmcnt(14)
	v_add_f32_e32 v118, v92, v41
	v_add_f32_e32 v119, v92, v40
	v_add_f32_e32 v41, v84, v118
	v_add_f32_e32 v40, v85, v119
	v_add_f32_e32 v120, v92, v43
	v_add_f32_e32 v121, v92, v42
	v_max3_f32 v84, v41, s7, v40
	v_add_f32_e32 v43, v86, v120
	v_add_f32_e32 v42, v87, v121
	v_add_f32_e32 v122, v92, v45
	v_add_f32_e32 v123, v92, v44
	v_max3_f32 v84, v84, v43, v42
	v_add_f32_e32 v45, v88, v122
	v_add_f32_e32 v44, v89, v123
	v_add_f32_e32 v124, v92, v47
	v_add_f32_e32 v125, v92, v46
	v_max3_f32 v84, v84, v45, v44
	v_add_f32_e32 v47, v90, v124
	v_add_f32_e32 v46, v91, v125
	v_add_f32_e32 v126, v92, v137
	v_add_f32_e32 v127, v92, v136
	v_max3_f32 v84, v84, v47, v46
	v_add_f32_e32 v85, v94, v126
	v_add_f32_e32 v86, v95, v127
	v_add_f32_e32 v136, v92, v165
	v_add_f32_e32 v137, v92, v164
	v_max3_f32 v84, v84, v85, v86
	v_add_f32_e32 v87, v96, v136
	v_add_f32_e32 v88, v97, v137
	s_waitcnt lgkmcnt(13)
	v_add_f32_e32 v163, v92, v167
	v_add_f32_e32 v164, v92, v166
	v_max3_f32 v84, v84, v87, v88
	v_add_f32_e32 v89, v98, v163
	v_add_f32_e32 v90, v99, v164
	s_waitcnt lgkmcnt(12)
	v_add_f32_e32 v165, v92, v169
	v_add_f32_e32 v166, v92, v168
	v_max3_f32 v84, v84, v89, v90
	v_add_f32_e32 v91, v100, v165
	v_add_f32_e32 v93, v101, v166
	s_waitcnt lgkmcnt(11)
	v_add_f32_e32 v167, v92, v171
	v_add_f32_e32 v168, v92, v170
	v_max3_f32 v84, v84, v91, v93
	v_add_f32_e32 v94, v102, v167
	v_add_f32_e32 v95, v103, v168
	s_waitcnt lgkmcnt(10)
	v_add_f32_e32 v169, v92, v173
	v_add_f32_e32 v170, v92, v172
	v_max3_f32 v84, v84, v94, v95
	v_add_f32_e32 v96, v104, v169
	v_add_f32_e32 v97, v105, v170
	s_waitcnt lgkmcnt(9)
	v_add_f32_e32 v98, v92, v39
	v_add_f32_e32 v99, v92, v38
	v_max3_f32 v84, v84, v96, v97
	v_add_f32_e32 v98, v106, v98
	v_add_f32_e32 v99, v107, v99
	s_waitcnt lgkmcnt(8)
	v_add_f32_e32 v100, v92, v37
	v_add_f32_e32 v101, v92, v36
	v_max3_f32 v84, v84, v98, v99
	v_add_f32_e32 v100, v108, v100
	v_add_f32_e32 v101, v109, v101
	s_waitcnt lgkmcnt(7)
	v_add_f32_e32 v171, 0, v175
	v_add_f32_e32 v172, 0, v174
	v_max3_f32 v84, v84, v100, v101
	v_add_f32_e32 v198, v110, v171
	v_add_f32_e32 v199, v111, v172
	s_waitcnt lgkmcnt(6)
	v_add_f32_e32 v173, 0, v177
	v_add_f32_e32 v174, 0, v176
	v_max3_f32 v84, v84, v198, v199
	v_add_f32_e32 v210, v112, v173
	v_add_f32_e32 v211, v113, v174
	s_waitcnt lgkmcnt(5)
	v_add_f32_e32 v175, 0, v179
	v_add_f32_e32 v176, 0, v178
	s_waitcnt lgkmcnt(3)
	v_add_f32_e32 v179, 0, v191
	v_max3_f32 v84, v84, v210, v211
	v_add_f32_e32 v212, v114, v175
	v_add_f32_e32 v213, v115, v176
	v_add_f32_e32 v177, 0, v189
	v_add_f32_e32 v178, 0, v188
	v_add_f32_e32 v191, v180, v179
	v_add_f32_e32 v180, 0, v190
	v_max3_f32 v84, v84, v212, v213
	v_add_f32_e32 v189, v116, v177
	v_add_f32_e32 v188, v117, v178
	v_add_f32_e32 v190, v181, v180
	s_waitcnt lgkmcnt(2)
	v_add_f32_e32 v181, 0, v193
	s_waitcnt lgkmcnt(1)
	v_add_f32_e32 v102, 0, v195
	v_max3_f32 v84, v84, v189, v188
	v_add_f32_e32 v193, v182, v181
	v_add_f32_e32 v182, 0, v192
	v_add_f32_e32 v184, v184, v102
	v_add_f32_e32 v102, 0, v194
	v_max3_f32 v84, v84, v191, v190
	v_add_f32_e32 v183, v183, v182
	v_add_f32_e32 v185, v185, v102
	s_waitcnt lgkmcnt(0)
	v_add_f32_e32 v102, 0, v197
	v_max3_f32 v84, v84, v193, v183
	v_add_f32_e32 v186, v186, v102
	v_add_f32_e32 v102, 0, v196
	v_max3_f32 v84, v84, v184, v185
	v_add_f32_e32 v187, v187, v102
	v_max3_f32 v84, v84, v186, v187
	ds_bpermute_b32 v102, v140, v84
	v_add_f32_e32 v52, v52, v118
	v_add_f32_e32 v53, v53, v119
	v_add_f32_e32 v54, v54, v120
	v_add_f32_e32 v55, v55, v121
	s_waitcnt lgkmcnt(0)
	v_max_f32_e32 v102, v102, v102
	v_max_f32_e32 v84, v84, v102
	ds_bpermute_b32 v102, v141, v84
	v_add_f32_e32 v56, v56, v122
	v_add_f32_e32 v57, v57, v123
	v_add_f32_e32 v58, v58, v124
	v_add_f32_e32 v59, v59, v125
	s_waitcnt lgkmcnt(0)
	v_max3_f32 v192, v84, v102, v133
	v_sub_f32_e32 v41, v41, v192
	v_exp_f32_e32 v110, v41
	v_sub_f32_e32 v40, v40, v192
	v_exp_f32_e32 v111, v40
	v_sub_f32_e32 v84, v187, v192
	v_add_f32_e32 v41, 0, v110
	v_exp_f32_e32 v84, v84
	v_add_f32_e32 v40, v111, v41
	v_sub_f32_e32 v41, v43, v192
	v_exp_f32_e32 v112, v41
	v_sub_f32_e32 v41, v42, v192
	v_exp_f32_e32 v113, v41
	v_sub_f32_e32 v41, v45, v192
	v_exp_f32_e32 v114, v41
	v_sub_f32_e32 v41, v44, v192
	v_exp_f32_e32 v115, v41
	v_sub_f32_e32 v41, v47, v192
	v_add_f32_e32 v40, v112, v40
	v_exp_f32_e32 v116, v41
	v_sub_f32_e32 v41, v46, v192
	v_add_f32_e32 v40, v113, v40
	v_exp_f32_e32 v117, v41
	v_sub_f32_e32 v41, v85, v192
	v_add_f32_e32 v40, v114, v40
	v_exp_f32_e32 v102, v41
	v_sub_f32_e32 v41, v86, v192
	v_add_f32_e32 v40, v115, v40
	v_exp_f32_e32 v103, v41
	v_sub_f32_e32 v41, v87, v192
	v_add_f32_e32 v40, v116, v40
	v_exp_f32_e32 v104, v41
	v_sub_f32_e32 v41, v88, v192
	v_add_f32_e32 v40, v117, v40
	v_exp_f32_e32 v105, v41
	v_sub_f32_e32 v41, v89, v192
	v_add_f32_e32 v40, v102, v40
	v_exp_f32_e32 v106, v41
	v_sub_f32_e32 v41, v90, v192
	v_add_f32_e32 v40, v103, v40
	v_exp_f32_e32 v107, v41
	v_sub_f32_e32 v41, v91, v192
	v_add_f32_e32 v40, v104, v40
	v_exp_f32_e32 v108, v41
	v_sub_f32_e32 v41, v93, v192
	v_add_f32_e32 v40, v105, v40
	v_exp_f32_e32 v109, v41
	v_sub_f32_e32 v41, v94, v192
	v_add_f32_e32 v40, v106, v40
	v_exp_f32_e32 v94, v41
	v_sub_f32_e32 v41, v95, v192
	v_add_f32_e32 v40, v107, v40
	v_exp_f32_e32 v95, v41
	v_sub_f32_e32 v41, v96, v192
	v_add_f32_e32 v40, v108, v40
	v_exp_f32_e32 v96, v41
	v_sub_f32_e32 v41, v97, v192
	v_add_f32_e32 v40, v109, v40
	v_exp_f32_e32 v97, v41
	v_sub_f32_e32 v41, v98, v192
	v_add_f32_e32 v40, v94, v40
	v_exp_f32_e32 v98, v41
	v_sub_f32_e32 v41, v99, v192
	v_add_f32_e32 v40, v95, v40
	v_exp_f32_e32 v99, v41
	v_sub_f32_e32 v41, v100, v192
	v_add_f32_e32 v40, v96, v40
	v_exp_f32_e32 v100, v41
	v_sub_f32_e32 v41, v101, v192
	v_add_f32_e32 v40, v97, v40
	v_exp_f32_e32 v101, v41
	v_sub_f32_e32 v41, v198, v192
	v_add_f32_e32 v40, v98, v40
	v_exp_f32_e32 v85, v41
	v_sub_f32_e32 v41, v199, v192
	v_add_f32_e32 v40, v99, v40
	v_exp_f32_e32 v86, v41
	v_sub_f32_e32 v41, v210, v192
	v_add_f32_e32 v40, v100, v40
	v_exp_f32_e32 v87, v41
	v_sub_f32_e32 v41, v211, v192
	v_add_f32_e32 v40, v101, v40
	v_exp_f32_e32 v88, v41
	v_sub_f32_e32 v41, v212, v192
	v_add_f32_e32 v40, v85, v40
	v_exp_f32_e32 v89, v41
	v_sub_f32_e32 v41, v213, v192
	v_add_f32_e32 v40, v86, v40
	v_exp_f32_e32 v90, v41
	v_sub_f32_e32 v41, v189, v192
	v_add_f32_e32 v40, v87, v40
	v_exp_f32_e32 v91, v41
	v_sub_f32_e32 v41, v188, v192
	v_add_f32_e32 v40, v88, v40
	v_exp_f32_e32 v93, v41
	v_sub_f32_e32 v41, v191, v192
	v_add_f32_e32 v40, v89, v40
	v_exp_f32_e32 v41, v41
	v_sub_f32_e32 v42, v190, v192
	v_add_f32_e32 v40, v90, v40
	v_exp_f32_e32 v42, v42
	v_sub_f32_e32 v43, v193, v192
	v_add_f32_e32 v40, v91, v40
	v_exp_f32_e32 v43, v43
	v_sub_f32_e32 v44, v183, v192
	v_add_f32_e32 v40, v93, v40
	v_exp_f32_e32 v44, v44
	v_sub_f32_e32 v45, v184, v192
	v_add_f32_e32 v40, v41, v40
	v_exp_f32_e32 v45, v45
	v_sub_f32_e32 v46, v185, v192
	v_add_f32_e32 v40, v42, v40
	v_exp_f32_e32 v46, v46
	v_sub_f32_e32 v47, v186, v192
	v_add_f32_e32 v40, v43, v40
	v_exp_f32_e32 v47, v47
	v_add_f32_e32 v40, v44, v40
	v_add_f32_e32 v40, v45, v40
	v_add_f32_e32 v40, v46, v40
	v_add_f32_e32 v40, v47, v40
	v_add_f32_e32 v40, v84, v40
	ds_bpermute_b32 v183, v140, v40
	v_add_f32_e32 v60, v60, v126
	v_add_f32_e32 v61, v61, v127
	v_add_f32_e32 v62, v62, v136
	v_add_f32_e32 v63, v63, v137
	s_waitcnt lgkmcnt(0)
	v_add_f32_e32 v40, v40, v183
	ds_bpermute_b32 v183, v141, v40
	v_add_f32_e32 v64, v64, v163
	v_add_f32_e32 v119, v65, v164
	v_add_f32_e32 v120, v67, v166
	v_add_f32_e32 v121, v68, v167
	s_waitcnt lgkmcnt(0)
	v_add_f32_e32 v40, v40, v183
	v_fma_f32 v183, v162, s6, -v192
	v_exp_f32_e32 v183, v183
	v_add_f32_e32 v122, v69, v168
	v_add_f32_e32 v123, v70, v169
	v_add_f32_e32 v124, v71, v170
	v_add_f32_e32 v40, v183, v40
	v_div_scale_f32 v183, s[0:1], v40, v40, 1.0
	v_rcp_f32_e32 v184, v183
	v_add_f32_e32 v39, 0, v39
	v_add_f32_e32 v38, 0, v38
	v_add_f32_e32 v39, v72, v39
	v_fma_f32 v185, -v183, v184, 1.0
	v_fmac_f32_e32 v184, v185, v184
	v_div_scale_f32 v185, vcc, 1.0, v40, 1.0
	v_mul_f32_e32 v186, v185, v184
	v_fma_f32 v187, -v183, v186, v185
	v_fmac_f32_e32 v186, v187, v184
	v_fma_f32 v183, -v183, v186, v185
	v_div_fmas_f32 v183, v183, v184, v186
	ds_read2_b32 v[184:185], v139 offset0:175 offset1:176
	ds_read2_b32 v[186:187], v139 offset0:173 offset1:174
	v_div_fixup_f32 v40, v183, v40, 1.0
	v_add_f32_e32 v38, v73, v38
	v_add_f32_e32 v37, 0, v37
	s_waitcnt lgkmcnt(1)
	v_add_f32_e32 v183, v92, v185
	v_add_f32_e32 v48, v48, v183
	v_add_f32_e32 v183, v92, v184
	s_waitcnt lgkmcnt(0)
	v_add_f32_e32 v184, v92, v187
	v_add_f32_e32 v49, v49, v183
	v_add_f32_e32 v50, v50, v184
	v_add_f32_e32 v184, v92, v186
	v_max3_f32 v183, v48, s7, v49
	v_add_f32_e32 v51, v51, v184
	v_max3_f32 v183, v183, v50, v51
	v_max3_f32 v118, v183, v52, v53
	v_max3_f32 v118, v118, v54, v55
	v_max3_f32 v118, v118, v56, v57
	v_max3_f32 v118, v118, v58, v59
	v_max3_f32 v118, v118, v60, v61
	v_max3_f32 v118, v118, v62, v63
	v_max3_f32 v65, v118, v64, v119
	v_add_f32_e32 v118, v66, v165
	v_max3_f32 v65, v65, v118, v120
	v_max3_f32 v65, v65, v121, v122
	v_max3_f32 v65, v65, v123, v124
	v_add_f32_e32 v36, 0, v36
	v_max3_f32 v65, v65, v39, v38
	v_add_f32_e32 v37, v74, v37
	v_add_f32_e32 v36, v75, v36
	v_max3_f32 v65, v65, v37, v36
	v_add_f32_e32 v125, v76, v171
	v_add_f32_e32 v126, v77, v172
	v_max3_f32 v65, v65, v125, v126
	v_add_f32_e32 v127, v78, v173
	v_add_f32_e32 v136, v79, v174
	v_max3_f32 v65, v65, v127, v136
	v_add_f32_e32 v137, v80, v175
	v_add_f32_e32 v81, v81, v176
	v_max3_f32 v65, v65, v137, v81
	v_add_f32_e32 v82, v82, v177
	v_add_f32_e32 v83, v83, v178
	v_max3_f32 v65, v65, v82, v83
	v_add_f32_e32 v32, v32, v179
	v_add_f32_e32 v163, v33, v180
	v_max3_f32 v33, v65, v32, v163
	v_add_f32_e32 v164, v34, v181
	v_add_f32_e32 v165, v35, v182
	v_max3_f32 v33, v33, v164, v165
	ds_bpermute_b32 v34, v140, v33
	v_cvt_pk_bf16_f32 v110, v110, v111
	v_cvt_pk_bf16_f32 v111, v112, v113
	v_cvt_pk_bf16_f32 v112, v114, v115
	v_cvt_pk_bf16_f32 v113, v116, v117
	s_waitcnt lgkmcnt(0)
	v_max_f32_e32 v34, v34, v34
	v_max_f32_e32 v33, v33, v34
	ds_bpermute_b32 v34, v141, v33
	s_waitcnt lgkmcnt(0)
	v_max3_f32 v166, v33, v34, v133
	v_sub_f32_e32 v33, v48, v166
	v_exp_f32_e32 v73, v33
	v_sub_f32_e32 v34, v49, v166
	v_exp_f32_e32 v74, v34
	v_sub_f32_e32 v34, v50, v166
	v_exp_f32_e32 v75, v34
	v_sub_f32_e32 v34, v51, v166
	v_exp_f32_e32 v76, v34
	v_sub_f32_e32 v34, v52, v166
	v_add_f32_e32 v33, 0, v73
	v_exp_f32_e32 v77, v34
	v_sub_f32_e32 v34, v53, v166
	v_add_f32_e32 v33, v74, v33
	v_exp_f32_e32 v78, v34
	v_sub_f32_e32 v34, v54, v166
	v_add_f32_e32 v33, v75, v33
	v_exp_f32_e32 v79, v34
	v_sub_f32_e32 v34, v55, v166
	v_add_f32_e32 v33, v76, v33
	v_exp_f32_e32 v80, v34
	v_sub_f32_e32 v34, v56, v166
	v_add_f32_e32 v33, v77, v33
	v_exp_f32_e32 v65, v34
	v_sub_f32_e32 v34, v57, v166
	v_add_f32_e32 v33, v78, v33
	v_exp_f32_e32 v66, v34
	v_sub_f32_e32 v34, v58, v166
	v_add_f32_e32 v33, v79, v33
	v_exp_f32_e32 v67, v34
	v_sub_f32_e32 v34, v59, v166
	v_add_f32_e32 v33, v80, v33
	v_exp_f32_e32 v68, v34
	v_sub_f32_e32 v34, v60, v166
	v_add_f32_e32 v33, v65, v33
	v_exp_f32_e32 v69, v34
	v_sub_f32_e32 v34, v61, v166
	v_add_f32_e32 v33, v66, v33
	v_exp_f32_e32 v70, v34
	v_sub_f32_e32 v34, v62, v166
	v_add_f32_e32 v33, v67, v33
	v_exp_f32_e32 v71, v34
	v_sub_f32_e32 v34, v63, v166
	v_add_f32_e32 v33, v68, v33
	v_exp_f32_e32 v72, v34
	v_sub_f32_e32 v34, v64, v166
	v_add_f32_e32 v33, v69, v33
	v_exp_f32_e32 v57, v34
	v_sub_f32_e32 v34, v119, v166
	v_add_f32_e32 v33, v70, v33
	v_exp_f32_e32 v58, v34
	v_sub_f32_e32 v34, v118, v166
	v_add_f32_e32 v33, v71, v33
	v_exp_f32_e32 v59, v34
	v_sub_f32_e32 v34, v120, v166
	v_add_f32_e32 v33, v72, v33
	v_exp_f32_e32 v60, v34
	v_sub_f32_e32 v34, v121, v166
	v_add_f32_e32 v33, v57, v33
	v_exp_f32_e32 v61, v34
	v_sub_f32_e32 v34, v122, v166
	v_add_f32_e32 v33, v58, v33
	v_exp_f32_e32 v62, v34
	v_sub_f32_e32 v34, v123, v166
	v_add_f32_e32 v33, v59, v33
	v_exp_f32_e32 v63, v34
	v_sub_f32_e32 v34, v124, v166
	v_add_f32_e32 v33, v60, v33
	v_exp_f32_e32 v64, v34
	v_sub_f32_e32 v34, v39, v166
	v_add_f32_e32 v33, v61, v33
	v_exp_f32_e32 v49, v34
	v_sub_f32_e32 v34, v38, v166
	v_add_f32_e32 v33, v62, v33
	v_exp_f32_e32 v50, v34
	v_sub_f32_e32 v34, v37, v166
	v_add_f32_e32 v33, v63, v33
	v_exp_f32_e32 v51, v34
	v_sub_f32_e32 v34, v36, v166
	v_add_f32_e32 v33, v64, v33
	v_exp_f32_e32 v52, v34
	v_sub_f32_e32 v34, v125, v166
	v_add_f32_e32 v33, v49, v33
	v_exp_f32_e32 v53, v34
	v_sub_f32_e32 v34, v126, v166
	v_add_f32_e32 v33, v50, v33
	v_exp_f32_e32 v54, v34
	v_sub_f32_e32 v34, v127, v166
	v_add_f32_e32 v33, v51, v33
	v_exp_f32_e32 v55, v34
	v_sub_f32_e32 v34, v136, v166
	v_add_f32_e32 v33, v52, v33
	v_exp_f32_e32 v56, v34
	v_add_f32_e32 v33, v53, v33
	v_add_f32_e32 v33, v54, v33
	v_add_f32_e32 v33, v55, v33
	v_add_f32_e32 v34, v56, v33
	v_sub_f32_e32 v33, v137, v166
	v_exp_f32_e32 v33, v33
	v_sub_f32_e32 v32, v32, v166
	v_sub_f32_e32 v39, v164, v166
	v_exp_f32_e32 v39, v39
	v_add_f32_e32 v35, v33, v34
	v_sub_f32_e32 v34, v81, v166
	v_exp_f32_e32 v34, v34
	v_sub_f32_e32 v48, v165, v166
	v_exp_f32_e32 v48, v48
	v_cvt_pk_bf16_f32 v74, v73, v74
	v_add_f32_e32 v36, v34, v35
	v_sub_f32_e32 v35, v82, v166
	v_exp_f32_e32 v35, v35
	v_cvt_pk_bf16_f32 v75, v75, v76
	v_cvt_pk_bf16_f32 v76, v77, v78
	v_cvt_pk_bf16_f32 v77, v79, v80
	ds_read_b128 v[172:175], v142 offset:62272
	v_add_f32_e32 v37, v35, v36
	v_sub_f32_e32 v36, v83, v166
	v_exp_f32_e32 v36, v36
	s_nop 0
	v_add_f32_e32 v38, v36, v37
	v_exp_f32_e32 v37, v32
	s_nop 0
	v_add_f32_e32 v32, v37, v38
	v_sub_f32_e32 v38, v163, v166
	v_exp_f32_e32 v38, v38
	s_nop 0
	v_add_f32_e32 v32, v38, v32
	v_add_f32_e32 v32, v39, v32
	v_add_f32_e32 v32, v48, v32
	ds_bpermute_b32 v81, v140, v32
	s_waitcnt lgkmcnt(0)
	v_add_f32_e32 v32, v32, v81
	ds_bpermute_b32 v81, v141, v32
	s_waitcnt lgkmcnt(0)
	v_add_f32_e32 v32, v32, v81
	v_fma_f32 v81, v162, s6, -v166
	v_exp_f32_e32 v81, v81
	ds_read_b128 v[164:167], v142 offset:53824
	s_waitcnt lgkmcnt(0)
	v_mfma_f32_16x16x32_bf16 v[168:171], v[164:167], v[110:113], 0
	v_add_f32_e32 v32, v81, v32
	v_div_scale_f32 v81, s[0:1], v32, v32, 1.0
	v_rcp_f32_e32 v82, v81
	v_mfma_f32_16x16x32_bf16 v[164:167], v[164:167], v[74:77], 0
	v_fma_f32 v83, -v81, v82, 1.0
	v_fmac_f32_e32 v82, v83, v82
	v_div_scale_f32 v83, vcc, 1.0, v32, 1.0
	v_mul_f32_e32 v118, v83, v82
	v_fma_f32 v119, -v81, v118, v83
	v_fmac_f32_e32 v118, v119, v82
	v_fma_f32 v81, -v81, v118, v83
	v_div_fmas_f32 v81, v81, v82, v118
	v_div_fixup_f32 v32, v81, v32, 1.0
	ds_read_b128 v[78:81], v142 offset:36928
	ds_read_b128 v[118:121], v142 offset:45376
	v_cvt_pk_bf16_f32 v102, v102, v103
	v_cvt_pk_bf16_f32 v103, v104, v105
	v_cvt_pk_bf16_f32 v104, v106, v107
	v_cvt_pk_bf16_f32 v105, v108, v109
	v_cvt_pk_bf16_f32 v66, v65, v66
	v_cvt_pk_bf16_f32 v67, v67, v68
	v_cvt_pk_bf16_f32 v68, v69, v70
	v_cvt_pk_bf16_f32 v69, v71, v72
	ds_read_b128 v[70:73], v142 offset:36992
	s_waitcnt lgkmcnt(2)
	v_mfma_f32_16x16x32_bf16 v[114:117], v[78:81], v[110:113], 0
	v_mfma_f32_16x16x32_bf16 v[78:81], v[78:81], v[74:77], 0
	s_waitcnt lgkmcnt(0)
	v_mfma_f32_16x16x32_bf16 v[106:109], v[70:73], v[102:105], v[114:117]
	v_mfma_f32_16x16x32_bf16 v[70:73], v[70:73], v[66:69], v[78:81]
	s_nop 4
	ds_read_b128 v[78:81], v142 offset:45440
	v_mfma_f32_16x16x32_bf16 v[122:125], v[118:121], v[110:113], 0
	v_mfma_f32_16x16x32_bf16 v[118:121], v[118:121], v[74:77], 0
	s_waitcnt lgkmcnt(0)
	v_mfma_f32_16x16x32_bf16 v[114:117], v[78:81], v[102:105], v[122:125]
	v_mfma_f32_16x16x32_bf16 v[78:81], v[78:81], v[66:69], v[118:121]
	s_nop 4
	ds_read_b128 v[118:121], v142 offset:53888
	s_waitcnt lgkmcnt(0)
	v_mfma_f32_16x16x32_bf16 v[122:125], v[118:121], v[102:105], v[168:171]
	v_mfma_f32_16x16x32_bf16 v[118:121], v[118:121], v[66:69], v[164:167]
	s_nop 2
	ds_read_b128 v[164:167], v142 offset:62336
	v_mfma_f32_16x16x32_bf16 v[74:77], v[172:175], v[74:77], 0
	s_waitcnt lgkmcnt(0)
	v_mfma_f32_16x16x32_bf16 v[66:69], v[164:167], v[66:69], v[74:77]
	v_cvt_pk_bf16_f32 v74, v94, v95
	v_cvt_pk_bf16_f32 v75, v96, v97
	v_cvt_pk_bf16_f32 v76, v98, v99
	v_cvt_pk_bf16_f32 v77, v100, v101
	v_cvt_pk_bf16_f32 v58, v57, v58
	v_cvt_pk_bf16_f32 v59, v59, v60
	v_cvt_pk_bf16_f32 v60, v61, v62
	v_cvt_pk_bf16_f32 v61, v63, v64
	ds_read_b128 v[62:65], v142 offset:37056
	v_mfma_f32_16x16x32_bf16 v[110:113], v[172:175], v[110:113], 0
	v_mfma_f32_16x16x32_bf16 v[102:105], v[164:167], v[102:105], v[110:113]
	s_nop 6
	ds_read_b128 v[110:113], v142 offset:62400
	s_waitcnt lgkmcnt(1)
	v_mfma_f32_16x16x32_bf16 v[94:97], v[62:65], v[74:77], v[106:109]
	v_mfma_f32_16x16x32_bf16 v[62:65], v[62:65], v[58:61], v[70:73]
	s_nop 2
	ds_read_b128 v[70:73], v142 offset:45504
	s_waitcnt lgkmcnt(0)
	v_mfma_f32_16x16x32_bf16 v[98:101], v[70:73], v[74:77], v[114:117]
	v_mfma_f32_16x16x32_bf16 v[70:73], v[70:73], v[58:61], v[78:81]
	s_nop 2
	ds_read_b128 v[78:81], v142 offset:53952
	s_waitcnt lgkmcnt(0)
	v_mfma_f32_16x16x32_bf16 v[106:109], v[78:81], v[74:77], v[122:125]
	v_mfma_f32_16x16x32_bf16 v[78:81], v[78:81], v[58:61], v[118:121]
	v_mfma_f32_16x16x32_bf16 v[58:61], v[110:113], v[58:61], v[66:69]
	v_cvt_pk_bf16_f32 v66, v85, v86
	v_cvt_pk_bf16_f32 v67, v87, v88
	v_cvt_pk_bf16_f32 v68, v89, v90
	v_cvt_pk_bf16_f32 v69, v91, v93
	v_cvt_pk_bf16_f32 v50, v49, v50
	v_cvt_pk_bf16_f32 v51, v51, v52
	v_cvt_pk_bf16_f32 v52, v53, v54
	v_cvt_pk_bf16_f32 v53, v55, v56
	ds_read_b128 v[54:57], v142 offset:37120
	s_waitcnt lgkmcnt(0)
	v_mfma_f32_16x16x32_bf16 v[86:89], v[54:57], v[66:69], v[94:97]
	v_mfma_f32_16x16x32_bf16 v[54:57], v[54:57], v[50:53], v[62:65]
	s_nop 2
	ds_read_b128 v[62:65], v142 offset:45568
	s_waitcnt lgkmcnt(0)
	v_mfma_f32_16x16x32_bf16 v[94:97], v[62:65], v[66:69], v[98:101]
	v_mfma_f32_16x16x32_bf16 v[62:65], v[62:65], v[50:53], v[70:73]
	s_nop 2
	ds_read_b128 v[70:73], v142 offset:54016
	s_waitcnt lgkmcnt(0)
	v_mfma_f32_16x16x32_bf16 v[98:101], v[70:73], v[66:69], v[106:109]
	v_mfma_f32_16x16x32_bf16 v[70:73], v[70:73], v[50:53], v[78:81]
	s_nop 2
	ds_read_b128 v[78:81], v142 offset:62464
	v_cvt_pk_bf16_f32 v42, v41, v42
	v_cvt_pk_bf16_f32 v43, v43, v44
	v_cvt_pk_bf16_f32 v44, v45, v46
	v_cvt_pk_bf16_f32 v45, v47, v84
	v_cvt_pk_bf16_f32 v34, v33, v34
	v_cvt_pk_bf16_f32 v35, v35, v36
	v_cvt_pk_bf16_f32 v36, v37, v38
	v_cvt_pk_bf16_f32 v37, v39, v48
	ds_read_b128 v[46:49], v142 offset:37184
	s_waitcnt lgkmcnt(1)
	v_mfma_f32_16x16x32_bf16 v[50:53], v[78:81], v[50:53], v[58:61]
	v_or_b32_e32 v38, 32, v132
	v_ashrrev_i32_e32 v39, 31, v38
	v_lshlrev_b64 v[38:39], 12, v[38:39]
	s_waitcnt lgkmcnt(0)
	v_mfma_f32_16x16x32_bf16 v[58:61], v[46:49], v[42:45], v[86:89]
	v_lshl_add_u64 v[38:39], v[134:135], 0, v[38:39]
	s_nop 6
	v_mfma_f32_16x16x32_bf16 v[46:49], v[46:49], v[34:37], v[54:57]
	s_nop 1
	ds_read_b128 v[54:57], v142 offset:45632
	v_mfma_f32_16x16x32_bf16 v[74:77], v[110:113], v[74:77], v[102:105]
	v_mfma_f32_16x16x32_bf16 v[66:69], v[78:81], v[66:69], v[74:77]
	s_waitcnt lgkmcnt(0)
	v_mfma_f32_16x16x32_bf16 v[74:77], v[54:57], v[42:45], v[94:97]
	v_mfma_f32_16x16x32_bf16 v[54:57], v[54:57], v[34:37], v[62:65]
	s_nop 2
	ds_read_b128 v[62:65], v142 offset:54080
	s_waitcnt lgkmcnt(0)
	v_mfma_f32_16x16x32_bf16 v[78:81], v[62:65], v[42:45], v[98:101]
	v_mfma_f32_16x16x32_bf16 v[62:65], v[62:65], v[34:37], v[70:73]
	s_nop 2
	ds_read_b128 v[70:73], v142 offset:62528
	s_waitcnt lgkmcnt(0)
	v_mfma_f32_16x16x32_bf16 v[34:37], v[70:73], v[34:37], v[50:53]
	v_mfma_f32_16x16x32_bf16 v[42:45], v[70:73], v[42:45], v[66:69]
	v_mul_f32_e32 v58, v40, v58
	v_mul_f32_e32 v59, v40, v59
	v_mul_f32_e32 v60, v40, v60
	v_mul_f32_e32 v61, v40, v61
	v_mul_f32_e32 v74, v40, v74
	v_mul_f32_e32 v75, v40, v75
	v_mul_f32_e32 v76, v40, v76
	v_mul_f32_e32 v77, v40, v77
	v_mul_f32_e32 v78, v40, v78
	v_mul_f32_e32 v79, v40, v79
	v_mul_f32_e32 v80, v40, v80
	v_mul_f32_e32 v81, v40, v81
	v_mul_f32_e32 v42, v40, v42
	v_mul_f32_e32 v43, v40, v43
	v_mul_f32_e32 v44, v40, v44
	v_mul_f32_e32 v45, v40, v45
	v_cvt_pk_bf16_f32 v58, v58, v59
	v_cvt_pk_bf16_f32 v59, v60, v61
	v_cvt_pk_bf16_f32 v60, v74, v75
	v_cvt_pk_bf16_f32 v61, v76, v77
	v_cvt_pk_bf16_f32 v78, v78, v79
	v_cvt_pk_bf16_f32 v79, v80, v81
	v_cvt_pk_bf16_f32 v80, v42, v43
	v_cvt_pk_bf16_f32 v81, v44, v45
	s_nop 1
	v_permlane16_swap_b32_e32 v58, v60
	v_permlane16_swap_b32_e32 v59, v61
	v_permlane16_swap_b32_e32 v78, v80
	v_permlane16_swap_b32_e32 v79, v81
	global_store_dwordx4 v[38:39], v[58:61], off
	global_store_dwordx4 v[38:39], v[78:81], off offset:64
	v_or_b32_e32 v38, 48, v132
	v_ashrrev_i32_e32 v39, 31, v38
	v_lshlrev_b64 v[38:39], 12, v[38:39]
	v_lshl_add_u64 v[38:39], v[134:135], 0, v[38:39]
	v_mul_f32_e32 v46, v32, v46
	v_mul_f32_e32 v47, v32, v47
	v_mul_f32_e32 v48, v32, v48
	v_mul_f32_e32 v49, v32, v49
	v_mul_f32_e32 v54, v32, v54
	v_mul_f32_e32 v55, v32, v55
	v_mul_f32_e32 v56, v32, v56
	v_mul_f32_e32 v57, v32, v57
	v_mul_f32_e32 v62, v32, v62
	v_mul_f32_e32 v63, v32, v63
	v_mul_f32_e32 v64, v32, v64
	v_mul_f32_e32 v65, v32, v65
	v_mul_f32_e32 v34, v32, v34
	v_mul_f32_e32 v35, v32, v35
	v_mul_f32_e32 v36, v32, v36
	v_mul_f32_e32 v37, v32, v37
	v_cvt_pk_bf16_f32 v46, v46, v47
	v_cvt_pk_bf16_f32 v47, v48, v49
	v_cvt_pk_bf16_f32 v48, v54, v55
	v_cvt_pk_bf16_f32 v49, v56, v57
	v_cvt_pk_bf16_f32 v62, v62, v63
	v_cvt_pk_bf16_f32 v63, v64, v65
	v_cvt_pk_bf16_f32 v64, v34, v35
	v_cvt_pk_bf16_f32 v65, v36, v37
	s_nop 1
	v_permlane16_swap_b32_e32 v46, v48
	v_permlane16_swap_b32_e32 v47, v49
	v_permlane16_swap_b32_e32 v62, v64
	v_permlane16_swap_b32_e32 v63, v65
	global_store_dwordx4 v[38:39], v[46:49], off
	global_store_dwordx4 v[38:39], v[62:65], off offset:64
	ds_read_b128 v[32:35], v153 offset:9216
	ds_read_b128 v[36:39], v153 offset:9280
	s_waitcnt vmcnt(15) lgkmcnt(1)
	v_mfma_f32_16x16x32_bf16 v[40:43], v[32:35], v[20:23], 0
	s_waitcnt vmcnt(13)
	v_mfma_f32_16x16x32_bf16 v[32:35], v[32:35], v[24:27], 0
	s_waitcnt lgkmcnt(0)
	v_mfma_f32_16x16x32_bf16 v[68:71], v[36:39], v[16:19], v[40:43]
	s_waitcnt vmcnt(12)
	v_mfma_f32_16x16x32_bf16 v[32:35], v[36:39], v[28:31], v[32:35]
	ds_read_b128 v[36:39], v153 offset:11520
	s_nop 0
	ds_read_b128 v[40:43], v153 offset:11584
	s_waitcnt lgkmcnt(1)
	v_mfma_f32_16x16x32_bf16 v[44:47], v[36:39], v[20:23], 0
	v_mfma_f32_16x16x32_bf16 v[36:39], v[36:39], v[24:27], 0
	s_waitcnt lgkmcnt(0)
	v_mfma_f32_16x16x32_bf16 v[72:75], v[40:43], v[16:19], v[44:47]
	v_mfma_f32_16x16x32_bf16 v[36:39], v[40:43], v[28:31], v[36:39]
	ds_read_b128 v[40:43], v153 offset:13824
	s_nop 2
	ds_read_b128 v[44:47], v153 offset:13888
	s_waitcnt lgkmcnt(1)
	v_mfma_f32_16x16x32_bf16 v[48:51], v[40:43], v[20:23], 0
	v_mfma_f32_16x16x32_bf16 v[40:43], v[40:43], v[24:27], 0
	s_waitcnt lgkmcnt(0)
	v_mfma_f32_16x16x32_bf16 v[76:79], v[44:47], v[16:19], v[48:51]
	v_mfma_f32_16x16x32_bf16 v[40:43], v[44:47], v[28:31], v[40:43]
	ds_read_b128 v[44:47], v153 offset:16128
	s_nop 2
	ds_read_b128 v[48:51], v153 offset:16192
	s_waitcnt lgkmcnt(1)
	v_mfma_f32_16x16x32_bf16 v[52:55], v[44:47], v[20:23], 0
	v_mfma_f32_16x16x32_bf16 v[44:47], v[44:47], v[24:27], 0
	s_waitcnt lgkmcnt(0)
	v_mfma_f32_16x16x32_bf16 v[80:83], v[48:51], v[16:19], v[52:55]
	v_mfma_f32_16x16x32_bf16 v[44:47], v[48:51], v[28:31], v[44:47]
	ds_read_b128 v[48:51], v153 offset:18432
	s_nop 2
	ds_read_b128 v[52:55], v153 offset:18496
	s_waitcnt lgkmcnt(1)
	v_mfma_f32_16x16x32_bf16 v[56:59], v[48:51], v[20:23], 0
	v_mfma_f32_16x16x32_bf16 v[48:51], v[48:51], v[24:27], 0
	s_waitcnt lgkmcnt(0)
	v_mfma_f32_16x16x32_bf16 v[84:87], v[52:55], v[16:19], v[56:59]
	v_mfma_f32_16x16x32_bf16 v[48:51], v[52:55], v[28:31], v[48:51]
	ds_read_b128 v[52:55], v153 offset:20736
	s_nop 2
	ds_read_b128 v[56:59], v153 offset:20800
	s_waitcnt lgkmcnt(1)
	v_mfma_f32_16x16x32_bf16 v[60:63], v[52:55], v[20:23], 0
	v_mfma_f32_16x16x32_bf16 v[52:55], v[52:55], v[24:27], 0
	s_waitcnt lgkmcnt(0)
	v_mfma_f32_16x16x32_bf16 v[88:91], v[56:59], v[16:19], v[60:63]
	v_mfma_f32_16x16x32_bf16 v[52:55], v[56:59], v[28:31], v[52:55]
	ds_read_b128 v[56:59], v153 offset:23040
	s_nop 2
	ds_read_b128 v[60:63], v153 offset:23104
	s_waitcnt lgkmcnt(1)
	v_mfma_f32_16x16x32_bf16 v[64:67], v[56:59], v[20:23], 0
	v_mfma_f32_16x16x32_bf16 v[56:59], v[56:59], v[24:27], 0
	s_waitcnt lgkmcnt(0)
	v_mfma_f32_16x16x32_bf16 v[94:97], v[60:63], v[16:19], v[64:67]
	v_mfma_f32_16x16x32_bf16 v[56:59], v[60:63], v[28:31], v[56:59]
	ds_read_b128 v[60:63], v153 offset:25344
	s_nop 2
	ds_read_b128 v[64:67], v153 offset:25408
	s_waitcnt lgkmcnt(1)
	v_mfma_f32_16x16x32_bf16 v[98:101], v[60:63], v[20:23], 0
	v_mfma_f32_16x16x32_bf16 v[60:63], v[60:63], v[24:27], 0
	s_waitcnt lgkmcnt(0)
	v_mfma_f32_16x16x32_bf16 v[98:101], v[64:67], v[16:19], v[98:101]
	v_mfma_f32_16x16x32_bf16 v[60:63], v[64:67], v[28:31], v[60:63]
	ds_read_b128 v[64:67], v153 offset:27648
	ds_read_b128 v[102:105], v153 offset:27712
	s_waitcnt lgkmcnt(1)
	v_mfma_f32_16x16x32_bf16 v[106:109], v[64:67], v[20:23], 0
	v_mfma_f32_16x16x32_bf16 v[64:67], v[64:67], v[24:27], 0
	s_waitcnt lgkmcnt(0)
	v_mfma_f32_16x16x32_bf16 v[164:167], v[102:105], v[16:19], v[106:109]
	v_mfma_f32_16x16x32_bf16 v[64:67], v[102:105], v[28:31], v[64:67]
	ds_read_b128 v[102:105], v153 offset:29952
	s_nop 2
	ds_read_b128 v[106:109], v153 offset:30016
	s_waitcnt lgkmcnt(1)
	v_mfma_f32_16x16x32_bf16 v[20:23], v[102:105], v[20:23], 0
	s_waitcnt lgkmcnt(0)
	v_mfma_f32_16x16x32_bf16 v[168:171], v[106:109], v[16:19], v[20:23]
	v_mfma_f32_16x16x32_bf16 v[16:19], v[102:105], v[24:27], 0
	v_mfma_f32_16x16x32_bf16 v[16:19], v[106:109], v[28:31], v[16:19]
	ds_read2_b32 v[24:25], v139 offset0:159 offset1:160
	ds_read2_b32 v[26:27], v139 offset0:157 offset1:158
	ds_read2_b32 v[28:29], v139 offset0:143 offset1:144
	ds_read2_b32 v[30:31], v139 offset0:141 offset1:142
	ds_read2_b32 v[112:113], v139 offset0:127 offset1:128
	ds_read2_b32 v[114:115], v139 offset0:125 offset1:126
	ds_read2_b32 v[22:23], v139 offset0:111 offset1:112
	ds_read2_b32 v[20:21], v139 offset0:109 offset1:110
	ds_read2_b32 v[116:117], v139 offset0:95 offset1:96
	ds_read2_b32 v[118:119], v139 offset0:93 offset1:94
	ds_read2_b32 v[120:121], v139 offset0:79 offset1:80
	ds_read2_b32 v[122:123], v139 offset0:77 offset1:78
	ds_read2_b32 v[124:125], v139 offset0:63 offset1:64
	ds_read2_b32 v[126:127], v139 offset0:61 offset1:62
	ds_read2_b32 v[136:137], v139 offset0:47 offset1:48
	ds_read2_b32 v[172:173], v139 offset0:45 offset1:46
	ds_read2_b32 v[174:175], v139 offset0:31 offset1:32
	ds_read2_b32 v[176:177], v139 offset0:29 offset1:30
	ds_read2_b32 v[178:179], v139 offset0:15 offset1:16
	ds_read2_b32 v[180:181], v139 offset0:13 offset1:14
	s_waitcnt lgkmcnt(14)
	v_add_f32_e32 v102, v92, v25
	v_add_f32_e32 v103, v92, v24
	v_add_f32_e32 v25, v68, v102
	v_add_f32_e32 v24, v69, v103
	v_add_f32_e32 v104, v92, v27
	v_add_f32_e32 v105, v92, v26
	v_max3_f32 v68, v25, s7, v24
	v_add_f32_e32 v27, v70, v104
	v_add_f32_e32 v26, v71, v105
	v_add_f32_e32 v106, v92, v29
	v_add_f32_e32 v107, v92, v28
	v_max3_f32 v68, v68, v27, v26
	v_add_f32_e32 v29, v72, v106
	v_add_f32_e32 v28, v73, v107
	v_add_f32_e32 v108, v92, v31
	v_add_f32_e32 v109, v92, v30
	v_max3_f32 v68, v68, v29, v28
	v_add_f32_e32 v31, v74, v108
	v_add_f32_e32 v30, v75, v109
	v_add_f32_e32 v110, v92, v113
	v_add_f32_e32 v111, v92, v112
	v_max3_f32 v68, v68, v31, v30
	v_add_f32_e32 v69, v76, v110
	v_add_f32_e32 v70, v77, v111
	v_add_f32_e32 v112, v92, v115
	v_add_f32_e32 v113, v92, v114
	v_max3_f32 v68, v68, v69, v70
	v_add_f32_e32 v71, v78, v112
	v_add_f32_e32 v72, v79, v113
	s_waitcnt lgkmcnt(13)
	v_add_f32_e32 v73, v92, v23
	v_add_f32_e32 v74, v92, v22
	v_max3_f32 v68, v68, v71, v72
	v_add_f32_e32 v73, v80, v73
	v_add_f32_e32 v74, v81, v74
	s_waitcnt lgkmcnt(12)
	v_add_f32_e32 v75, v92, v21
	v_add_f32_e32 v76, v92, v20
	v_max3_f32 v68, v68, v73, v74
	v_add_f32_e32 v75, v82, v75
	v_add_f32_e32 v76, v83, v76
	s_waitcnt lgkmcnt(11)
	v_add_f32_e32 v114, 0, v117
	v_add_f32_e32 v115, 0, v116
	v_max3_f32 v68, v68, v75, v76
	v_add_f32_e32 v77, v84, v114
	v_add_f32_e32 v78, v85, v115
	s_waitcnt lgkmcnt(10)
	v_add_f32_e32 v116, 0, v119
	v_add_f32_e32 v117, 0, v118
	v_max3_f32 v68, v68, v77, v78
	v_add_f32_e32 v79, v86, v116
	v_add_f32_e32 v80, v87, v117
	s_waitcnt lgkmcnt(9)
	v_add_f32_e32 v118, 0, v121
	v_add_f32_e32 v119, 0, v120
	v_max3_f32 v68, v68, v79, v80
	v_add_f32_e32 v81, v88, v118
	v_add_f32_e32 v82, v89, v119
	s_waitcnt lgkmcnt(8)
	v_add_f32_e32 v120, 0, v123
	v_add_f32_e32 v121, 0, v122
	v_max3_f32 v68, v68, v81, v82
	v_add_f32_e32 v83, v90, v120
	v_add_f32_e32 v84, v91, v121
	s_waitcnt lgkmcnt(7)
	v_add_f32_e32 v122, 0, v125
	v_add_f32_e32 v123, 0, v124
	v_max3_f32 v68, v68, v83, v84
	v_add_f32_e32 v182, v94, v122
	v_add_f32_e32 v183, v95, v123
	s_waitcnt lgkmcnt(6)
	v_add_f32_e32 v124, 0, v127
	v_add_f32_e32 v125, 0, v126
	v_max3_f32 v68, v68, v182, v183
	v_add_f32_e32 v184, v96, v124
	v_add_f32_e32 v185, v97, v125
	s_waitcnt lgkmcnt(5)
	v_add_f32_e32 v126, 0, v137
	v_add_f32_e32 v127, 0, v136
	s_waitcnt lgkmcnt(3)
	v_add_f32_e32 v163, 0, v175
	v_max3_f32 v68, v68, v184, v185
	v_add_f32_e32 v186, v98, v126
	v_add_f32_e32 v187, v99, v127
	v_add_f32_e32 v136, 0, v173
	v_add_f32_e32 v137, 0, v172
	v_add_f32_e32 v175, v164, v163
	v_add_f32_e32 v164, 0, v174
	v_max3_f32 v68, v68, v186, v187
	v_add_f32_e32 v173, v100, v136
	v_add_f32_e32 v172, v101, v137
	v_add_f32_e32 v174, v165, v164
	s_waitcnt lgkmcnt(2)
	v_add_f32_e32 v165, 0, v177
	s_waitcnt lgkmcnt(1)
	v_add_f32_e32 v85, 0, v179
	v_max3_f32 v68, v68, v173, v172
	v_add_f32_e32 v177, v166, v165
	v_add_f32_e32 v166, 0, v176
	v_add_f32_e32 v168, v168, v85
	v_add_f32_e32 v85, 0, v178
	v_max3_f32 v68, v68, v175, v174
	v_add_f32_e32 v167, v167, v166
	v_add_f32_e32 v169, v169, v85
	s_waitcnt lgkmcnt(0)
	v_add_f32_e32 v85, 0, v181
	v_max3_f32 v68, v68, v177, v167
	v_add_f32_e32 v170, v170, v85
	v_add_f32_e32 v85, 0, v180
	v_max3_f32 v68, v68, v168, v169
	v_add_f32_e32 v171, v171, v85
	v_max3_f32 v68, v68, v170, v171
	ds_bpermute_b32 v85, v140, v68
	v_add_f32_e32 v36, v36, v102
	v_add_f32_e32 v37, v37, v103
	v_add_f32_e32 v38, v38, v104
	v_add_f32_e32 v39, v39, v105
	s_waitcnt lgkmcnt(0)
	v_max_f32_e32 v85, v85, v85
	v_max_f32_e32 v68, v68, v85
	ds_bpermute_b32 v85, v141, v68
	v_add_f32_e32 v40, v40, v106
	v_add_f32_e32 v41, v41, v107
	v_add_f32_e32 v42, v42, v108
	v_add_f32_e32 v43, v43, v109
	s_waitcnt lgkmcnt(0)
	v_max3_f32 v176, v68, v85, v133
	v_sub_f32_e32 v25, v25, v176
	v_exp_f32_e32 v94, v25
	v_sub_f32_e32 v24, v24, v176
	v_exp_f32_e32 v95, v24
	v_sub_f32_e32 v68, v171, v176
	v_add_f32_e32 v25, 0, v94
	v_exp_f32_e32 v68, v68
	v_add_f32_e32 v24, v95, v25
	v_sub_f32_e32 v25, v27, v176
	v_exp_f32_e32 v96, v25
	v_sub_f32_e32 v25, v26, v176
	v_exp_f32_e32 v97, v25
	v_sub_f32_e32 v25, v29, v176
	v_exp_f32_e32 v98, v25
	v_sub_f32_e32 v25, v28, v176
	v_exp_f32_e32 v99, v25
	v_sub_f32_e32 v25, v31, v176
	v_add_f32_e32 v24, v96, v24
	v_exp_f32_e32 v100, v25
	v_sub_f32_e32 v25, v30, v176
	v_add_f32_e32 v24, v97, v24
	v_exp_f32_e32 v101, v25
	v_sub_f32_e32 v25, v69, v176
	v_add_f32_e32 v24, v98, v24
	v_exp_f32_e32 v85, v25
	v_sub_f32_e32 v25, v70, v176
	v_add_f32_e32 v24, v99, v24
	v_exp_f32_e32 v86, v25
	v_sub_f32_e32 v25, v71, v176
	v_add_f32_e32 v24, v100, v24
	v_exp_f32_e32 v87, v25
	v_sub_f32_e32 v25, v72, v176
	v_add_f32_e32 v24, v101, v24
	v_exp_f32_e32 v88, v25
	v_sub_f32_e32 v25, v73, v176
	v_add_f32_e32 v24, v85, v24
	v_exp_f32_e32 v89, v25
	v_sub_f32_e32 v25, v74, v176
	v_add_f32_e32 v24, v86, v24
	v_exp_f32_e32 v90, v25
	v_sub_f32_e32 v25, v75, v176
	v_add_f32_e32 v24, v87, v24
	v_exp_f32_e32 v91, v25
	v_sub_f32_e32 v25, v76, v176
	v_add_f32_e32 v24, v88, v24
	v_exp_f32_e32 v93, v25
	v_sub_f32_e32 v25, v77, v176
	v_add_f32_e32 v24, v89, v24
	v_exp_f32_e32 v77, v25
	v_sub_f32_e32 v25, v78, v176
	v_add_f32_e32 v24, v90, v24
	v_exp_f32_e32 v78, v25
	v_sub_f32_e32 v25, v79, v176
	v_add_f32_e32 v24, v91, v24
	v_exp_f32_e32 v79, v25
	v_sub_f32_e32 v25, v80, v176
	v_add_f32_e32 v24, v93, v24
	v_exp_f32_e32 v80, v25
	v_sub_f32_e32 v25, v81, v176
	v_add_f32_e32 v24, v77, v24
	v_exp_f32_e32 v81, v25
	v_sub_f32_e32 v25, v82, v176
	v_add_f32_e32 v24, v78, v24
	v_exp_f32_e32 v82, v25
	v_sub_f32_e32 v25, v83, v176
	v_add_f32_e32 v24, v79, v24
	v_exp_f32_e32 v83, v25
	v_sub_f32_e32 v25, v84, v176
	v_add_f32_e32 v24, v80, v24
	v_exp_f32_e32 v84, v25
	v_sub_f32_e32 v25, v182, v176
	v_add_f32_e32 v24, v81, v24
	v_exp_f32_e32 v69, v25
	v_sub_f32_e32 v25, v183, v176
	v_add_f32_e32 v24, v82, v24
	v_exp_f32_e32 v70, v25
	v_sub_f32_e32 v25, v184, v176
	v_add_f32_e32 v24, v83, v24
	v_exp_f32_e32 v71, v25
	v_sub_f32_e32 v25, v185, v176
	v_add_f32_e32 v24, v84, v24
	v_exp_f32_e32 v72, v25
	v_sub_f32_e32 v25, v186, v176
	v_add_f32_e32 v24, v69, v24
	v_exp_f32_e32 v73, v25
	v_sub_f32_e32 v25, v187, v176
	v_add_f32_e32 v24, v70, v24
	v_exp_f32_e32 v74, v25
	v_sub_f32_e32 v25, v173, v176
	v_add_f32_e32 v24, v71, v24
	v_exp_f32_e32 v75, v25
	v_sub_f32_e32 v25, v172, v176
	v_add_f32_e32 v24, v72, v24
	v_exp_f32_e32 v76, v25
	v_sub_f32_e32 v25, v175, v176
	v_add_f32_e32 v24, v73, v24
	v_exp_f32_e32 v25, v25
	v_sub_f32_e32 v26, v174, v176
	v_add_f32_e32 v24, v74, v24
	v_exp_f32_e32 v26, v26
	v_sub_f32_e32 v27, v177, v176
	v_add_f32_e32 v24, v75, v24
	v_exp_f32_e32 v27, v27
	v_sub_f32_e32 v28, v167, v176
	v_add_f32_e32 v24, v76, v24
	v_exp_f32_e32 v28, v28
	v_sub_f32_e32 v29, v168, v176
	v_add_f32_e32 v24, v25, v24
	v_exp_f32_e32 v29, v29
	v_sub_f32_e32 v30, v169, v176
	v_add_f32_e32 v24, v26, v24
	v_exp_f32_e32 v30, v30
	v_sub_f32_e32 v31, v170, v176
	v_add_f32_e32 v24, v27, v24
	v_exp_f32_e32 v31, v31
	v_add_f32_e32 v24, v28, v24
	v_add_f32_e32 v24, v29, v24
	v_add_f32_e32 v24, v30, v24
	v_add_f32_e32 v24, v31, v24
	v_add_f32_e32 v24, v68, v24
	ds_bpermute_b32 v167, v140, v24
	v_add_f32_e32 v44, v44, v110
	v_add_f32_e32 v45, v45, v111
	v_add_f32_e32 v46, v46, v112
	v_add_f32_e32 v47, v47, v113
	s_waitcnt lgkmcnt(0)
	v_add_f32_e32 v24, v24, v167
	ds_bpermute_b32 v167, v141, v24
	v_add_f32_e32 v23, 0, v23
	v_add_f32_e32 v22, 0, v22
	v_add_f32_e32 v23, v48, v23
	v_add_f32_e32 v22, v49, v22
	s_waitcnt lgkmcnt(0)
	v_add_f32_e32 v24, v24, v167
	v_fma_f32 v167, v162, s6, -v176
	v_exp_f32_e32 v167, v167
	v_add_f32_e32 v21, 0, v21
	v_add_f32_e32 v20, 0, v20
	v_add_f32_e32 v21, v50, v21
	v_add_f32_e32 v24, v167, v24
	v_div_scale_f32 v167, s[0:1], v24, v24, 1.0
	v_rcp_f32_e32 v168, v167
	v_add_f32_e32 v20, v51, v20
	v_add_f32_e32 v103, v53, v115
	v_add_f32_e32 v104, v54, v116
	v_fma_f32 v169, -v167, v168, 1.0
	v_fmac_f32_e32 v168, v169, v168
	v_div_scale_f32 v169, vcc, 1.0, v24, 1.0
	v_mul_f32_e32 v170, v169, v168
	v_fma_f32 v171, -v167, v170, v169
	v_fmac_f32_e32 v170, v171, v168
	v_fma_f32 v167, -v167, v170, v169
	v_div_fmas_f32 v167, v167, v168, v170
	ds_read2_b32 v[168:169], v139 offset0:175 offset1:176
	ds_read2_b32 v[170:171], v139 offset0:173 offset1:174
	v_div_fixup_f32 v24, v167, v24, 1.0
	v_add_f32_e32 v105, v55, v117
	v_add_f32_e32 v106, v56, v118
	s_waitcnt lgkmcnt(1)
	v_add_f32_e32 v167, v92, v169
	v_add_f32_e32 v32, v32, v167
	v_add_f32_e32 v167, v92, v168
	s_waitcnt lgkmcnt(0)
	v_add_f32_e32 v168, v92, v171
	v_add_f32_e32 v33, v33, v167
	v_add_f32_e32 v34, v34, v168
	v_add_f32_e32 v168, v92, v170
	v_max3_f32 v167, v32, s7, v33
	v_add_f32_e32 v35, v35, v168
	v_max3_f32 v167, v167, v34, v35
	v_max3_f32 v102, v167, v36, v37
	v_max3_f32 v102, v102, v38, v39
	v_max3_f32 v102, v102, v40, v41
	v_max3_f32 v102, v102, v42, v43
	v_max3_f32 v102, v102, v44, v45
	v_max3_f32 v102, v102, v46, v47
	v_max3_f32 v48, v102, v23, v22
	v_max3_f32 v48, v48, v21, v20
	v_add_f32_e32 v102, v52, v114
	v_max3_f32 v48, v48, v102, v103
	v_max3_f32 v48, v48, v104, v105
	v_add_f32_e32 v107, v57, v119
	v_max3_f32 v48, v48, v106, v107
	v_add_f32_e32 v108, v58, v120
	v_add_f32_e32 v109, v59, v121
	v_max3_f32 v48, v48, v108, v109
	v_add_f32_e32 v110, v60, v122
	v_add_f32_e32 v111, v61, v123
	v_max3_f32 v48, v48, v110, v111
	v_add_f32_e32 v112, v62, v124
	v_add_f32_e32 v113, v63, v125
	v_max3_f32 v48, v48, v112, v113
	v_add_f32_e32 v114, v64, v126
	v_add_f32_e32 v65, v65, v127
	v_max3_f32 v48, v48, v114, v65
	v_add_f32_e32 v66, v66, v136
	v_add_f32_e32 v67, v67, v137
	v_max3_f32 v48, v48, v66, v67
	v_add_f32_e32 v16, v16, v163
	v_add_f32_e32 v115, v17, v164
	v_max3_f32 v17, v48, v16, v115
	v_add_f32_e32 v116, v18, v165
	v_add_f32_e32 v117, v19, v166
	v_max3_f32 v17, v17, v116, v117
	ds_bpermute_b32 v18, v140, v17
	v_cvt_pk_bf16_f32 v94, v94, v95
	v_cvt_pk_bf16_f32 v95, v96, v97
	v_cvt_pk_bf16_f32 v96, v98, v99
	v_cvt_pk_bf16_f32 v97, v100, v101
	s_waitcnt lgkmcnt(0)
	v_max_f32_e32 v18, v18, v18
	v_max_f32_e32 v17, v17, v18
	ds_bpermute_b32 v18, v141, v17
	s_waitcnt lgkmcnt(0)
	v_max3_f32 v118, v17, v18, v133
	v_sub_f32_e32 v17, v32, v118
	v_exp_f32_e32 v57, v17
	v_sub_f32_e32 v18, v33, v118
	v_exp_f32_e32 v58, v18
	v_sub_f32_e32 v18, v34, v118
	v_exp_f32_e32 v59, v18
	v_sub_f32_e32 v18, v35, v118
	v_exp_f32_e32 v60, v18
	v_sub_f32_e32 v18, v36, v118
	v_add_f32_e32 v17, 0, v57
	v_exp_f32_e32 v61, v18
	v_sub_f32_e32 v18, v37, v118
	v_add_f32_e32 v17, v58, v17
	v_exp_f32_e32 v62, v18
	v_sub_f32_e32 v18, v38, v118
	v_add_f32_e32 v17, v59, v17
	v_exp_f32_e32 v63, v18
	v_sub_f32_e32 v18, v39, v118
	v_add_f32_e32 v17, v60, v17
	v_exp_f32_e32 v64, v18
	v_sub_f32_e32 v18, v40, v118
	v_add_f32_e32 v17, v61, v17
	v_exp_f32_e32 v49, v18
	v_sub_f32_e32 v18, v41, v118
	v_add_f32_e32 v17, v62, v17
	v_exp_f32_e32 v50, v18
	v_sub_f32_e32 v18, v42, v118
	v_add_f32_e32 v17, v63, v17
	v_exp_f32_e32 v51, v18
	v_sub_f32_e32 v18, v43, v118
	v_add_f32_e32 v17, v64, v17
	v_exp_f32_e32 v52, v18
	v_sub_f32_e32 v18, v44, v118
	v_add_f32_e32 v17, v49, v17
	v_exp_f32_e32 v53, v18
	v_sub_f32_e32 v18, v45, v118
	v_add_f32_e32 v17, v50, v17
	v_exp_f32_e32 v54, v18
	v_sub_f32_e32 v18, v46, v118
	v_add_f32_e32 v17, v51, v17
	v_exp_f32_e32 v55, v18
	v_sub_f32_e32 v18, v47, v118
	v_add_f32_e32 v17, v52, v17
	v_exp_f32_e32 v56, v18
	v_sub_f32_e32 v18, v23, v118
	v_add_f32_e32 v17, v53, v17
	v_exp_f32_e32 v41, v18
	v_sub_f32_e32 v18, v22, v118
	v_add_f32_e32 v17, v54, v17
	v_exp_f32_e32 v42, v18
	v_sub_f32_e32 v18, v21, v118
	v_add_f32_e32 v17, v55, v17
	v_exp_f32_e32 v43, v18
	v_sub_f32_e32 v18, v20, v118
	v_add_f32_e32 v17, v56, v17
	v_exp_f32_e32 v44, v18
	v_sub_f32_e32 v18, v102, v118
	v_add_f32_e32 v17, v41, v17
	v_exp_f32_e32 v45, v18
	v_sub_f32_e32 v18, v103, v118
	v_add_f32_e32 v17, v42, v17
	v_exp_f32_e32 v46, v18
	v_sub_f32_e32 v18, v104, v118
	v_add_f32_e32 v17, v43, v17
	v_exp_f32_e32 v47, v18
	v_sub_f32_e32 v18, v105, v118
	v_add_f32_e32 v17, v44, v17
	v_exp_f32_e32 v48, v18
	v_sub_f32_e32 v18, v106, v118
	v_add_f32_e32 v17, v45, v17
	v_exp_f32_e32 v33, v18
	v_sub_f32_e32 v18, v107, v118
	v_add_f32_e32 v17, v46, v17
	v_exp_f32_e32 v34, v18
	v_sub_f32_e32 v18, v108, v118
	v_add_f32_e32 v17, v47, v17
	v_exp_f32_e32 v35, v18
	v_sub_f32_e32 v18, v109, v118
	v_add_f32_e32 v17, v48, v17
	v_exp_f32_e32 v36, v18
	v_sub_f32_e32 v18, v110, v118
	v_add_f32_e32 v17, v33, v17
	v_exp_f32_e32 v37, v18
	v_sub_f32_e32 v18, v111, v118
	v_add_f32_e32 v17, v34, v17
	v_exp_f32_e32 v38, v18
	v_sub_f32_e32 v18, v112, v118
	v_add_f32_e32 v17, v35, v17
	v_exp_f32_e32 v39, v18
	v_sub_f32_e32 v18, v113, v118
	v_add_f32_e32 v17, v36, v17
	v_exp_f32_e32 v40, v18
	v_add_f32_e32 v17, v37, v17
	v_add_f32_e32 v17, v38, v17
	v_add_f32_e32 v17, v39, v17
	v_add_f32_e32 v18, v40, v17
	v_sub_f32_e32 v17, v114, v118
	v_exp_f32_e32 v17, v17
	v_sub_f32_e32 v16, v16, v118
	v_sub_f32_e32 v23, v116, v118
	v_exp_f32_e32 v23, v23
	v_add_f32_e32 v19, v17, v18
	v_sub_f32_e32 v18, v65, v118
	v_exp_f32_e32 v18, v18
	v_sub_f32_e32 v32, v117, v118
	v_exp_f32_e32 v32, v32
	v_cvt_pk_bf16_f32 v58, v57, v58
	v_add_f32_e32 v20, v18, v19
	v_sub_f32_e32 v19, v66, v118
	v_exp_f32_e32 v19, v19
	v_cvt_pk_bf16_f32 v59, v59, v60
	v_cvt_pk_bf16_f32 v60, v61, v62
	v_cvt_pk_bf16_f32 v61, v63, v64
	ds_read_b128 v[110:113], v142 offset:53888
	v_add_f32_e32 v21, v19, v20
	v_sub_f32_e32 v20, v67, v118
	v_exp_f32_e32 v20, v20
	s_nop 0
	v_add_f32_e32 v22, v20, v21
	v_exp_f32_e32 v21, v16
	s_nop 0
	v_add_f32_e32 v16, v21, v22
	v_sub_f32_e32 v22, v115, v118
	v_exp_f32_e32 v22, v22
	s_nop 0
	v_add_f32_e32 v16, v22, v16
	v_add_f32_e32 v16, v23, v16
	v_add_f32_e32 v16, v32, v16
	ds_bpermute_b32 v65, v140, v16
	s_waitcnt lgkmcnt(0)
	v_add_f32_e32 v16, v16, v65
	ds_bpermute_b32 v65, v141, v16
	s_waitcnt lgkmcnt(0)
	v_add_f32_e32 v16, v16, v65
	v_fma_f32 v65, v162, s6, -v118
	v_exp_f32_e32 v65, v65
	ds_read_b128 v[118:121], v142 offset:62336
	v_mfma_f32_16x16x32_bf16 v[114:117], v[110:113], v[94:97], 0
	v_add_f32_e32 v16, v65, v16
	v_div_scale_f32 v65, s[0:1], v16, v16, 1.0
	v_rcp_f32_e32 v66, v65
	v_mfma_f32_16x16x32_bf16 v[110:113], v[110:113], v[58:61], 0
	v_fma_f32 v67, -v65, v66, 1.0
	v_fmac_f32_e32 v66, v67, v66
	v_div_scale_f32 v67, vcc, 1.0, v16, 1.0
	v_mul_f32_e32 v102, v67, v66
	v_fma_f32 v103, -v65, v102, v67
	v_fmac_f32_e32 v102, v103, v66
	v_fma_f32 v65, -v65, v102, v67
	v_div_fmas_f32 v65, v65, v66, v102
	v_div_fixup_f32 v16, v65, v16, 1.0
	ds_read_b128 v[62:65], v142 offset:36992
	ds_read_b128 v[102:105], v142 offset:45440
	v_cvt_pk_bf16_f32 v86, v85, v86
	v_cvt_pk_bf16_f32 v87, v87, v88
	v_cvt_pk_bf16_f32 v88, v89, v90
	v_cvt_pk_bf16_f32 v89, v91, v93
	v_cvt_pk_bf16_f32 v50, v49, v50
	v_cvt_pk_bf16_f32 v51, v51, v52
	v_cvt_pk_bf16_f32 v52, v53, v54
	v_cvt_pk_bf16_f32 v53, v55, v56
	ds_read_b128 v[54:57], v142 offset:37056
	s_waitcnt lgkmcnt(2)
	v_mfma_f32_16x16x32_bf16 v[98:101], v[62:65], v[94:97], 0
	v_mfma_f32_16x16x32_bf16 v[62:65], v[62:65], v[58:61], 0
	s_waitcnt lgkmcnt(0)
	v_mfma_f32_16x16x32_bf16 v[98:101], v[54:57], v[86:89], v[98:101]
	v_mfma_f32_16x16x32_bf16 v[54:57], v[54:57], v[50:53], v[62:65]
	s_nop 4
	ds_read_b128 v[62:65], v142 offset:45504
	v_mfma_f32_16x16x32_bf16 v[106:109], v[102:105], v[94:97], 0
	v_mfma_f32_16x16x32_bf16 v[102:105], v[102:105], v[58:61], 0
	s_waitcnt lgkmcnt(0)
	v_mfma_f32_16x16x32_bf16 v[106:109], v[62:65], v[86:89], v[106:109]
	v_mfma_f32_16x16x32_bf16 v[62:65], v[62:65], v[50:53], v[102:105]
	s_nop 4
	ds_read_b128 v[102:105], v142 offset:53952
	s_waitcnt lgkmcnt(0)
	v_mfma_f32_16x16x32_bf16 v[114:117], v[102:105], v[86:89], v[114:117]
	v_mfma_f32_16x16x32_bf16 v[102:105], v[102:105], v[50:53], v[110:113]
	s_nop 2
	ds_read_b128 v[110:113], v142 offset:62400
	v_mfma_f32_16x16x32_bf16 v[58:61], v[118:121], v[58:61], 0
	s_waitcnt lgkmcnt(0)
	v_mfma_f32_16x16x32_bf16 v[50:53], v[110:113], v[50:53], v[58:61]
	v_cvt_pk_bf16_f32 v58, v77, v78
	v_cvt_pk_bf16_f32 v59, v79, v80
	v_cvt_pk_bf16_f32 v60, v81, v82
	v_cvt_pk_bf16_f32 v61, v83, v84
	v_cvt_pk_bf16_f32 v42, v41, v42
	v_cvt_pk_bf16_f32 v43, v43, v44
	v_cvt_pk_bf16_f32 v44, v45, v46
	v_cvt_pk_bf16_f32 v45, v47, v48
	ds_read_b128 v[46:49], v142 offset:37120
	s_waitcnt lgkmcnt(0)
	s_nop 3
	v_mfma_f32_16x16x32_bf16 v[78:81], v[46:49], v[58:61], v[98:101]
	s_nop 2
	ds_read_b128 v[98:101], v142 offset:62464
	v_mfma_f32_16x16x32_bf16 v[46:49], v[46:49], v[42:45], v[54:57]
	s_nop 2
	ds_read_b128 v[54:57], v142 offset:45568
	s_waitcnt lgkmcnt(0)
	v_mfma_f32_16x16x32_bf16 v[82:85], v[54:57], v[58:61], v[106:109]
	v_mfma_f32_16x16x32_bf16 v[54:57], v[54:57], v[42:45], v[62:65]
	s_nop 2
	ds_read_b128 v[62:65], v142 offset:54016
	v_mfma_f32_16x16x32_bf16 v[94:97], v[118:121], v[94:97], 0
	v_mfma_f32_16x16x32_bf16 v[86:89], v[110:113], v[86:89], v[94:97]
	s_waitcnt lgkmcnt(0)
	v_mfma_f32_16x16x32_bf16 v[94:97], v[62:65], v[58:61], v[114:117]
	v_mfma_f32_16x16x32_bf16 v[62:65], v[62:65], v[42:45], v[102:105]
	v_mfma_f32_16x16x32_bf16 v[42:45], v[98:101], v[42:45], v[50:53]
	v_cvt_pk_bf16_f32 v50, v69, v70
	v_cvt_pk_bf16_f32 v51, v71, v72
	v_cvt_pk_bf16_f32 v52, v73, v74
	v_cvt_pk_bf16_f32 v53, v75, v76
	v_cvt_pk_bf16_f32 v34, v33, v34
	v_cvt_pk_bf16_f32 v35, v35, v36
	v_cvt_pk_bf16_f32 v36, v37, v38
	v_cvt_pk_bf16_f32 v37, v39, v40
	ds_read_b128 v[38:41], v142 offset:37184
	s_waitcnt lgkmcnt(0)
	v_mfma_f32_16x16x32_bf16 v[70:73], v[38:41], v[50:53], v[78:81]
	v_mfma_f32_16x16x32_bf16 v[38:41], v[38:41], v[34:37], v[46:49]
	s_nop 2
	ds_read_b128 v[46:49], v142 offset:45632
	s_waitcnt lgkmcnt(0)
	v_mfma_f32_16x16x32_bf16 v[74:77], v[46:49], v[50:53], v[82:85]
	v_mfma_f32_16x16x32_bf16 v[46:49], v[46:49], v[34:37], v[54:57]
	s_nop 2
	ds_read_b128 v[54:57], v142 offset:54080
	s_waitcnt lgkmcnt(0)
	v_mfma_f32_16x16x32_bf16 v[78:81], v[54:57], v[50:53], v[94:97]
	v_mfma_f32_16x16x32_bf16 v[54:57], v[54:57], v[34:37], v[62:65]
	s_nop 2
	ds_read_b128 v[62:65], v142 offset:62528
	v_cvt_pk_bf16_f32 v26, v25, v26
	v_cvt_pk_bf16_f32 v27, v27, v28
	v_cvt_pk_bf16_f32 v28, v29, v30
	v_cvt_pk_bf16_f32 v29, v31, v68
	v_cvt_pk_bf16_f32 v18, v17, v18
	v_cvt_pk_bf16_f32 v19, v19, v20
	v_cvt_pk_bf16_f32 v20, v21, v22
	v_cvt_pk_bf16_f32 v21, v23, v32
	ds_read_b128 v[30:33], v142 offset:37248
	s_waitcnt lgkmcnt(1)
	v_mfma_f32_16x16x32_bf16 v[34:37], v[62:65], v[34:37], v[42:45]
	v_or_b32_e32 v22, 64, v132
	v_ashrrev_i32_e32 v23, 31, v22
	v_lshlrev_b64 v[22:23], 12, v[22:23]
	s_waitcnt lgkmcnt(0)
	v_mfma_f32_16x16x32_bf16 v[42:45], v[30:33], v[26:29], v[70:73]
	v_lshl_add_u64 v[22:23], v[134:135], 0, v[22:23]
	s_nop 6
	v_mfma_f32_16x16x32_bf16 v[30:33], v[30:33], v[18:21], v[38:41]
	s_nop 1
	ds_read_b128 v[38:41], v142 offset:45696
	v_mfma_f32_16x16x32_bf16 v[58:61], v[98:101], v[58:61], v[86:89]
	v_mfma_f32_16x16x32_bf16 v[50:53], v[62:65], v[50:53], v[58:61]
	s_waitcnt lgkmcnt(0)
	v_mfma_f32_16x16x32_bf16 v[58:61], v[38:41], v[26:29], v[74:77]
	v_mfma_f32_16x16x32_bf16 v[38:41], v[38:41], v[18:21], v[46:49]
	s_nop 2
	ds_read_b128 v[46:49], v142 offset:54144
	s_waitcnt lgkmcnt(0)
	v_mfma_f32_16x16x32_bf16 v[62:65], v[46:49], v[26:29], v[78:81]
	v_mfma_f32_16x16x32_bf16 v[46:49], v[46:49], v[18:21], v[54:57]
	s_nop 2
	ds_read_b128 v[54:57], v142 offset:62592
	s_waitcnt lgkmcnt(0)
	v_mfma_f32_16x16x32_bf16 v[18:21], v[54:57], v[18:21], v[34:37]
	v_mfma_f32_16x16x32_bf16 v[26:29], v[54:57], v[26:29], v[50:53]
	v_mul_f32_e32 v42, v24, v42
	v_mul_f32_e32 v43, v24, v43
	v_mul_f32_e32 v44, v24, v44
	v_mul_f32_e32 v45, v24, v45
	v_mul_f32_e32 v58, v24, v58
	v_mul_f32_e32 v59, v24, v59
	v_mul_f32_e32 v60, v24, v60
	v_mul_f32_e32 v61, v24, v61
	v_mul_f32_e32 v62, v24, v62
	v_mul_f32_e32 v63, v24, v63
	v_mul_f32_e32 v64, v24, v64
	v_mul_f32_e32 v65, v24, v65
	v_mul_f32_e32 v26, v24, v26
	v_mul_f32_e32 v27, v24, v27
	v_mul_f32_e32 v28, v24, v28
	v_mul_f32_e32 v29, v24, v29
	v_cvt_pk_bf16_f32 v42, v42, v43
	v_cvt_pk_bf16_f32 v43, v44, v45
	v_cvt_pk_bf16_f32 v44, v58, v59
	v_cvt_pk_bf16_f32 v45, v60, v61
	v_cvt_pk_bf16_f32 v62, v62, v63
	v_cvt_pk_bf16_f32 v63, v64, v65
	v_cvt_pk_bf16_f32 v64, v26, v27
	v_cvt_pk_bf16_f32 v65, v28, v29
	s_nop 1
	v_permlane16_swap_b32_e32 v42, v44
	v_permlane16_swap_b32_e32 v43, v45
	v_permlane16_swap_b32_e32 v62, v64
	v_permlane16_swap_b32_e32 v63, v65
	global_store_dwordx4 v[22:23], v[42:45], off
	global_store_dwordx4 v[22:23], v[62:65], off offset:64
	v_or_b32_e32 v22, 0x50, v132
	v_ashrrev_i32_e32 v23, 31, v22
	v_lshlrev_b64 v[22:23], 12, v[22:23]
	v_lshl_add_u64 v[22:23], v[134:135], 0, v[22:23]
	v_mul_f32_e32 v30, v16, v30
	v_mul_f32_e32 v31, v16, v31
	v_mul_f32_e32 v32, v16, v32
	v_mul_f32_e32 v33, v16, v33
	v_mul_f32_e32 v38, v16, v38
	v_mul_f32_e32 v39, v16, v39
	v_mul_f32_e32 v40, v16, v40
	v_mul_f32_e32 v41, v16, v41
	v_mul_f32_e32 v46, v16, v46
	v_mul_f32_e32 v47, v16, v47
	v_mul_f32_e32 v48, v16, v48
	v_mul_f32_e32 v49, v16, v49
	v_mul_f32_e32 v18, v16, v18
	v_mul_f32_e32 v19, v16, v19
	v_mul_f32_e32 v20, v16, v20
	v_mul_f32_e32 v21, v16, v21
	v_cvt_pk_bf16_f32 v30, v30, v31
	v_cvt_pk_bf16_f32 v31, v32, v33
	v_cvt_pk_bf16_f32 v32, v38, v39
	v_cvt_pk_bf16_f32 v33, v40, v41
	v_cvt_pk_bf16_f32 v46, v46, v47
	v_cvt_pk_bf16_f32 v47, v48, v49
	v_cvt_pk_bf16_f32 v48, v18, v19
	v_cvt_pk_bf16_f32 v49, v20, v21
	s_nop 1
	v_permlane16_swap_b32_e32 v30, v32
	v_permlane16_swap_b32_e32 v31, v33
	v_permlane16_swap_b32_e32 v46, v48
	v_permlane16_swap_b32_e32 v47, v49
	global_store_dwordx4 v[22:23], v[30:33], off
	global_store_dwordx4 v[22:23], v[46:49], off offset:64
	ds_read_b128 v[16:19], v153 offset:13824
	ds_read_b128 v[20:23], v153 offset:13888
	s_waitcnt vmcnt(15) lgkmcnt(1)
	v_mfma_f32_16x16x32_bf16 v[24:27], v[16:19], v[4:7], 0
	s_waitcnt vmcnt(13)
	v_mfma_f32_16x16x32_bf16 v[16:19], v[16:19], v[8:11], 0
	s_waitcnt lgkmcnt(0)
	v_mfma_f32_16x16x32_bf16 v[52:55], v[20:23], v[0:3], v[24:27]
	s_waitcnt vmcnt(12)
	v_mfma_f32_16x16x32_bf16 v[16:19], v[20:23], v[12:15], v[16:19]
	ds_read_b128 v[20:23], v153 offset:16128
	s_nop 0
	ds_read_b128 v[24:27], v153 offset:16192
	s_waitcnt lgkmcnt(1)
	v_mfma_f32_16x16x32_bf16 v[28:31], v[20:23], v[4:7], 0
	v_mfma_f32_16x16x32_bf16 v[20:23], v[20:23], v[8:11], 0
	s_waitcnt lgkmcnt(0)
	v_mfma_f32_16x16x32_bf16 v[56:59], v[24:27], v[0:3], v[28:31]
	v_mfma_f32_16x16x32_bf16 v[20:23], v[24:27], v[12:15], v[20:23]
	ds_read_b128 v[24:27], v153 offset:18432
	s_nop 2
	ds_read_b128 v[28:31], v153 offset:18496
	s_waitcnt lgkmcnt(1)
	v_mfma_f32_16x16x32_bf16 v[32:35], v[24:27], v[4:7], 0
	v_mfma_f32_16x16x32_bf16 v[24:27], v[24:27], v[8:11], 0
	s_waitcnt lgkmcnt(0)
	v_mfma_f32_16x16x32_bf16 v[60:63], v[28:31], v[0:3], v[32:35]
	v_mfma_f32_16x16x32_bf16 v[24:27], v[28:31], v[12:15], v[24:27]
	ds_read_b128 v[28:31], v153 offset:20736
	s_nop 2
	ds_read_b128 v[32:35], v153 offset:20800
	s_waitcnt lgkmcnt(1)
	v_mfma_f32_16x16x32_bf16 v[36:39], v[28:31], v[4:7], 0
	v_mfma_f32_16x16x32_bf16 v[28:31], v[28:31], v[8:11], 0
	s_waitcnt lgkmcnt(0)
	v_mfma_f32_16x16x32_bf16 v[64:67], v[32:35], v[0:3], v[36:39]
	v_mfma_f32_16x16x32_bf16 v[28:31], v[32:35], v[12:15], v[28:31]
	ds_read_b128 v[32:35], v153 offset:23040
	s_nop 2
	ds_read_b128 v[36:39], v153 offset:23104
	s_waitcnt lgkmcnt(1)
	v_mfma_f32_16x16x32_bf16 v[40:43], v[32:35], v[4:7], 0
	v_mfma_f32_16x16x32_bf16 v[32:35], v[32:35], v[8:11], 0
	s_waitcnt lgkmcnt(0)
	v_mfma_f32_16x16x32_bf16 v[68:71], v[36:39], v[0:3], v[40:43]
	v_mfma_f32_16x16x32_bf16 v[32:35], v[36:39], v[12:15], v[32:35]
	ds_read_b128 v[36:39], v153 offset:25344
	s_nop 2
	ds_read_b128 v[40:43], v153 offset:25408
	s_waitcnt lgkmcnt(1)
	v_mfma_f32_16x16x32_bf16 v[44:47], v[36:39], v[4:7], 0
	v_mfma_f32_16x16x32_bf16 v[36:39], v[36:39], v[8:11], 0
	s_waitcnt lgkmcnt(0)
	v_mfma_f32_16x16x32_bf16 v[72:75], v[40:43], v[0:3], v[44:47]
	v_mfma_f32_16x16x32_bf16 v[36:39], v[40:43], v[12:15], v[36:39]
	ds_read_b128 v[40:43], v153 offset:27648
	s_nop 2
	ds_read_b128 v[44:47], v153 offset:27712
	s_waitcnt lgkmcnt(1)
	v_mfma_f32_16x16x32_bf16 v[48:51], v[40:43], v[4:7], 0
	v_mfma_f32_16x16x32_bf16 v[40:43], v[40:43], v[8:11], 0
	s_waitcnt lgkmcnt(0)
	v_mfma_f32_16x16x32_bf16 v[76:79], v[44:47], v[0:3], v[48:51]
	v_mfma_f32_16x16x32_bf16 v[40:43], v[44:47], v[12:15], v[40:43]
	ds_read_b128 v[44:47], v153 offset:29952
	s_nop 2
	ds_read_b128 v[48:51], v153 offset:30016
	s_waitcnt lgkmcnt(1)
	v_mfma_f32_16x16x32_bf16 v[80:83], v[44:47], v[4:7], 0
	v_mfma_f32_16x16x32_bf16 v[44:47], v[44:47], v[8:11], 0
	s_waitcnt lgkmcnt(0)
	v_mfma_f32_16x16x32_bf16 v[80:83], v[48:51], v[0:3], v[80:83]
	v_mfma_f32_16x16x32_bf16 v[44:47], v[48:51], v[12:15], v[44:47]
	ds_read_b128 v[48:51], v153 offset:32256
	ds_read_b128 v[84:87], v153 offset:32320
	s_waitcnt lgkmcnt(1)
	v_mfma_f32_16x16x32_bf16 v[88:91], v[48:51], v[4:7], 0
	v_mfma_f32_16x16x32_bf16 v[48:51], v[48:51], v[8:11], 0
	s_waitcnt lgkmcnt(0)
	v_mfma_f32_16x16x32_bf16 v[116:119], v[84:87], v[0:3], v[88:91]
	v_mfma_f32_16x16x32_bf16 v[48:51], v[84:87], v[12:15], v[48:51]
	ds_read_b128 v[84:87], v153 offset:34560
	s_nop 2
	ds_read_b128 v[88:91], v153 offset:34624
	s_waitcnt lgkmcnt(1)
	v_mfma_f32_16x16x32_bf16 v[4:7], v[84:87], v[4:7], 0
	s_waitcnt lgkmcnt(0)
	v_mfma_f32_16x16x32_bf16 v[120:123], v[88:91], v[0:3], v[4:7]
	v_mfma_f32_16x16x32_bf16 v[0:3], v[84:87], v[8:11], 0
	v_mfma_f32_16x16x32_bf16 v[0:3], v[88:91], v[12:15], v[0:3]
	ds_read2_b32 v[8:9], v139 offset0:159 offset1:160
	ds_read2_b32 v[10:11], v139 offset0:157 offset1:158
	s_nop 1
	ds_read2_b32 v[6:7], v139 offset0:143 offset1:144
	ds_read2_b32 v[4:5], v139 offset0:141 offset1:142
	ds_read2_b32 v[12:13], v139 offset0:127 offset1:128
	ds_read2_b32 v[14:15], v139 offset0:125 offset1:126
	ds_read2_b32 v[96:97], v139 offset0:111 offset1:112
	ds_read2_b32 v[98:99], v139 offset0:109 offset1:110
	ds_read2_b32 v[100:101], v139 offset0:95 offset1:96
	ds_read2_b32 v[102:103], v139 offset0:93 offset1:94
	ds_read2_b32 v[104:105], v139 offset0:79 offset1:80
	ds_read2_b32 v[106:107], v139 offset0:77 offset1:78
	ds_read2_b32 v[108:109], v139 offset0:63 offset1:64
	ds_read2_b32 v[110:111], v139 offset0:61 offset1:62
	ds_read2_b32 v[112:113], v139 offset0:47 offset1:48
	ds_read2_b32 v[114:115], v139 offset0:45 offset1:46
	ds_read2_b32 v[124:125], v139 offset0:31 offset1:32
	ds_read2_b32 v[126:127], v139 offset0:29 offset1:30
	ds_read2_b32 v[136:137], v139 offset0:15 offset1:16
	ds_read2_b32 v[164:165], v139 offset0:13 offset1:14
	s_waitcnt lgkmcnt(14)
	v_add_f32_e32 v85, v92, v9
	v_add_f32_e32 v86, v92, v8
	v_add_f32_e32 v9, v52, v85
	v_add_f32_e32 v8, v53, v86
	v_add_f32_e32 v87, v92, v11
	v_add_f32_e32 v88, v92, v10
	v_max3_f32 v52, v9, s7, v8
	v_add_f32_e32 v11, v54, v87
	v_add_f32_e32 v10, v55, v88
	v_add_f32_e32 v53, v92, v7
	v_add_f32_e32 v54, v92, v6
	v_max3_f32 v52, v52, v11, v10
	v_add_f32_e32 v53, v56, v53
	v_add_f32_e32 v54, v57, v54
	v_add_f32_e32 v55, v92, v5
	v_add_f32_e32 v56, v92, v4
	v_max3_f32 v52, v52, v53, v54
	v_add_f32_e32 v55, v58, v55
	v_add_f32_e32 v56, v59, v56
	v_add_f32_e32 v89, 0, v13
	v_add_f32_e32 v90, 0, v12
	v_max3_f32 v52, v52, v55, v56
	v_add_f32_e32 v13, v60, v89
	v_add_f32_e32 v12, v61, v90
	v_add_f32_e32 v91, 0, v15
	v_add_f32_e32 v93, 0, v14
	v_max3_f32 v52, v52, v13, v12
	v_add_f32_e32 v15, v62, v91
	v_add_f32_e32 v14, v63, v93
	s_waitcnt lgkmcnt(13)
	v_add_f32_e32 v94, 0, v97
	v_add_f32_e32 v95, 0, v96
	v_max3_f32 v52, v52, v15, v14
	v_add_f32_e32 v57, v64, v94
	v_add_f32_e32 v58, v65, v95
	s_waitcnt lgkmcnt(12)
	v_add_f32_e32 v96, 0, v99
	v_add_f32_e32 v97, 0, v98
	v_max3_f32 v52, v52, v57, v58
	v_add_f32_e32 v59, v66, v96
	v_add_f32_e32 v60, v67, v97
	s_waitcnt lgkmcnt(11)
	v_add_f32_e32 v98, 0, v101
	v_add_f32_e32 v99, 0, v100
	v_max3_f32 v52, v52, v59, v60
	v_add_f32_e32 v61, v68, v98
	v_add_f32_e32 v62, v69, v99
	s_waitcnt lgkmcnt(10)
	v_add_f32_e32 v100, 0, v103
	v_add_f32_e32 v101, 0, v102
	v_max3_f32 v52, v52, v61, v62
	v_add_f32_e32 v63, v70, v100
	v_add_f32_e32 v64, v71, v101
	s_waitcnt lgkmcnt(9)
	v_add_f32_e32 v102, 0, v105
	v_add_f32_e32 v103, 0, v104
	v_max3_f32 v52, v52, v63, v64
	v_add_f32_e32 v65, v72, v102
	v_add_f32_e32 v66, v73, v103
	s_waitcnt lgkmcnt(8)
	v_add_f32_e32 v104, 0, v107
	v_add_f32_e32 v105, 0, v106
	v_max3_f32 v52, v52, v65, v66
	v_add_f32_e32 v67, v74, v104
	v_add_f32_e32 v68, v75, v105
	s_waitcnt lgkmcnt(7)
	v_add_f32_e32 v106, 0, v109
	v_add_f32_e32 v107, 0, v108
	v_max3_f32 v52, v52, v67, v68
	v_add_f32_e32 v163, v76, v106
	v_add_f32_e32 v166, v77, v107
	s_waitcnt lgkmcnt(6)
	v_add_f32_e32 v108, 0, v111
	v_add_f32_e32 v109, 0, v110
	v_max3_f32 v52, v52, v163, v166
	v_add_f32_e32 v167, v78, v108
	v_add_f32_e32 v168, v79, v109
	s_waitcnt lgkmcnt(5)
	v_add_f32_e32 v110, 0, v113
	v_add_f32_e32 v111, 0, v112
	v_max3_f32 v52, v52, v167, v168
	v_add_f32_e32 v169, v80, v110
	v_add_f32_e32 v170, v81, v111
	s_waitcnt lgkmcnt(4)
	v_add_f32_e32 v112, 0, v115
	v_add_f32_e32 v113, 0, v114
	v_max3_f32 v52, v52, v169, v170
	v_add_f32_e32 v171, v82, v112
	v_add_f32_e32 v172, v83, v113
	s_waitcnt lgkmcnt(3)
	v_add_f32_e32 v114, 0, v125
	v_add_f32_e32 v115, 0, v124
	s_waitcnt lgkmcnt(1)
	v_add_f32_e32 v69, 0, v137
	v_max3_f32 v52, v52, v171, v172
	v_add_f32_e32 v125, v116, v114
	v_add_f32_e32 v124, v117, v115
	v_add_f32_e32 v116, 0, v127
	v_add_f32_e32 v117, 0, v126
	v_add_f32_e32 v120, v120, v69
	v_add_f32_e32 v69, 0, v136
	v_max3_f32 v52, v52, v125, v124
	v_add_f32_e32 v118, v118, v116
	v_add_f32_e32 v119, v119, v117
	v_add_f32_e32 v121, v121, v69
	s_waitcnt lgkmcnt(0)
	v_add_f32_e32 v69, 0, v165
	v_max3_f32 v52, v52, v118, v119
	v_add_f32_e32 v122, v122, v69
	v_add_f32_e32 v69, 0, v164
	v_max3_f32 v52, v52, v120, v121
	v_add_f32_e32 v123, v123, v69
	v_max3_f32 v52, v52, v122, v123
	ds_bpermute_b32 v69, v140, v52
	v_add_f32_e32 v20, v20, v85
	v_add_f32_e32 v21, v21, v86
	v_add_f32_e32 v22, v22, v87
	v_add_f32_e32 v23, v23, v88
	s_waitcnt lgkmcnt(0)
	v_max_f32_e32 v69, v69, v69
	v_max_f32_e32 v52, v52, v69
	ds_bpermute_b32 v69, v141, v52
	v_add_f32_e32 v7, 0, v7
	v_add_f32_e32 v6, 0, v6
	v_add_f32_e32 v7, v24, v7
	v_add_f32_e32 v6, v25, v6
	s_waitcnt lgkmcnt(0)
	v_max3_f32 v126, v52, v69, v133
	v_sub_f32_e32 v9, v9, v126
	v_exp_f32_e32 v77, v9
	v_sub_f32_e32 v8, v8, v126
	v_exp_f32_e32 v78, v8
	v_sub_f32_e32 v52, v123, v126
	v_add_f32_e32 v9, 0, v77
	v_exp_f32_e32 v52, v52
	v_add_f32_e32 v8, v78, v9
	v_sub_f32_e32 v9, v11, v126
	v_exp_f32_e32 v79, v9
	v_sub_f32_e32 v9, v10, v126
	v_exp_f32_e32 v80, v9
	v_sub_f32_e32 v9, v53, v126
	v_exp_f32_e32 v81, v9
	v_sub_f32_e32 v9, v54, v126
	v_exp_f32_e32 v82, v9
	v_sub_f32_e32 v9, v55, v126
	v_add_f32_e32 v8, v79, v8
	v_exp_f32_e32 v83, v9
	v_sub_f32_e32 v9, v56, v126
	v_add_f32_e32 v8, v80, v8
	v_exp_f32_e32 v84, v9
	v_sub_f32_e32 v9, v13, v126
	v_add_f32_e32 v8, v81, v8
	v_exp_f32_e32 v69, v9
	v_sub_f32_e32 v9, v12, v126
	v_add_f32_e32 v8, v82, v8
	v_exp_f32_e32 v70, v9
	v_sub_f32_e32 v9, v15, v126
	v_add_f32_e32 v8, v83, v8
	v_exp_f32_e32 v71, v9
	v_sub_f32_e32 v9, v14, v126
	v_add_f32_e32 v8, v84, v8
	v_exp_f32_e32 v72, v9
	v_sub_f32_e32 v9, v57, v126
	v_add_f32_e32 v8, v69, v8
	v_exp_f32_e32 v73, v9
	v_sub_f32_e32 v9, v58, v126
	v_add_f32_e32 v8, v70, v8
	v_exp_f32_e32 v74, v9
	v_sub_f32_e32 v9, v59, v126
	v_add_f32_e32 v8, v71, v8
	v_exp_f32_e32 v75, v9
	v_sub_f32_e32 v9, v60, v126
	v_add_f32_e32 v8, v72, v8
	v_exp_f32_e32 v76, v9
	v_sub_f32_e32 v9, v61, v126
	v_add_f32_e32 v8, v73, v8
	v_exp_f32_e32 v61, v9
	v_sub_f32_e32 v9, v62, v126
	v_add_f32_e32 v8, v74, v8
	v_exp_f32_e32 v62, v9
	v_sub_f32_e32 v9, v63, v126
	v_add_f32_e32 v8, v75, v8
	v_exp_f32_e32 v63, v9
	v_sub_f32_e32 v9, v64, v126
	v_add_f32_e32 v8, v76, v8
	v_exp_f32_e32 v64, v9
	v_sub_f32_e32 v9, v65, v126
	v_add_f32_e32 v8, v61, v8
	v_exp_f32_e32 v65, v9
	v_sub_f32_e32 v9, v66, v126
	v_add_f32_e32 v8, v62, v8
	v_exp_f32_e32 v66, v9
	v_sub_f32_e32 v9, v67, v126
	v_add_f32_e32 v8, v63, v8
	v_exp_f32_e32 v67, v9
	v_sub_f32_e32 v9, v68, v126
	v_add_f32_e32 v8, v64, v8
	v_exp_f32_e32 v68, v9
	v_sub_f32_e32 v9, v163, v126
	v_add_f32_e32 v8, v65, v8
	v_exp_f32_e32 v53, v9
	v_sub_f32_e32 v9, v166, v126
	v_add_f32_e32 v8, v66, v8
	v_exp_f32_e32 v54, v9
	v_sub_f32_e32 v9, v167, v126
	v_add_f32_e32 v8, v67, v8
	v_exp_f32_e32 v55, v9
	v_sub_f32_e32 v9, v168, v126
	v_add_f32_e32 v8, v68, v8
	v_exp_f32_e32 v56, v9
	v_sub_f32_e32 v9, v169, v126
	v_add_f32_e32 v8, v53, v8
	v_exp_f32_e32 v57, v9
	v_sub_f32_e32 v9, v170, v126
	v_add_f32_e32 v8, v54, v8
	v_exp_f32_e32 v58, v9
	v_sub_f32_e32 v9, v171, v126
	v_add_f32_e32 v8, v55, v8
	v_exp_f32_e32 v59, v9
	v_sub_f32_e32 v9, v172, v126
	v_add_f32_e32 v8, v56, v8
	v_exp_f32_e32 v60, v9
	v_sub_f32_e32 v9, v125, v126
	v_add_f32_e32 v8, v57, v8
	v_exp_f32_e32 v9, v9
	v_sub_f32_e32 v10, v124, v126
	v_add_f32_e32 v8, v58, v8
	v_exp_f32_e32 v10, v10
	v_sub_f32_e32 v11, v118, v126
	v_add_f32_e32 v8, v59, v8
	v_exp_f32_e32 v11, v11
	v_sub_f32_e32 v12, v119, v126
	v_add_f32_e32 v8, v60, v8
	v_exp_f32_e32 v12, v12
	v_sub_f32_e32 v13, v120, v126
	v_add_f32_e32 v8, v9, v8
	v_exp_f32_e32 v13, v13
	v_sub_f32_e32 v14, v121, v126
	v_add_f32_e32 v8, v10, v8
	v_exp_f32_e32 v14, v14
	v_sub_f32_e32 v15, v122, v126
	v_add_f32_e32 v8, v11, v8
	v_exp_f32_e32 v15, v15
	v_add_f32_e32 v8, v12, v8
	v_add_f32_e32 v8, v13, v8
	v_add_f32_e32 v8, v14, v8
	v_add_f32_e32 v8, v15, v8
	v_add_f32_e32 v8, v52, v8
	ds_bpermute_b32 v118, v140, v8
	v_add_f32_e32 v5, 0, v5
	v_add_f32_e32 v4, 0, v4
	v_add_f32_e32 v5, v26, v5
	v_add_f32_e32 v4, v27, v4
	s_waitcnt lgkmcnt(0)
	v_add_f32_e32 v8, v8, v118
	ds_bpermute_b32 v118, v141, v8
	v_add_f32_e32 v25, v28, v89
	v_add_f32_e32 v26, v29, v90
	v_add_f32_e32 v27, v30, v91
	v_add_f32_e32 v28, v31, v93
	s_waitcnt lgkmcnt(0)
	v_add_f32_e32 v8, v8, v118
	v_fma_f32 v118, v162, s6, -v126
	v_exp_f32_e32 v118, v118
	v_add_f32_e32 v29, v32, v94
	v_add_f32_e32 v30, v33, v95
	v_add_f32_e32 v31, v34, v96
	v_add_f32_e32 v8, v118, v8
	v_div_scale_f32 v118, s[0:1], v8, v8, 1.0
	v_rcp_f32_e32 v119, v118
	v_add_f32_e32 v32, v35, v97
	v_add_f32_e32 v86, v37, v99
	v_add_f32_e32 v87, v38, v100
	v_fma_f32 v120, -v118, v119, 1.0
	v_fmac_f32_e32 v119, v120, v119
	v_div_scale_f32 v120, vcc, 1.0, v8, 1.0
	v_mul_f32_e32 v121, v120, v119
	v_fma_f32 v122, -v118, v121, v120
	v_fmac_f32_e32 v121, v122, v119
	v_fma_f32 v118, -v118, v121, v120
	v_div_fmas_f32 v118, v118, v119, v121
	v_div_fixup_f32 v8, v118, v8, 1.0
	ds_read2_b32 v[118:119], v139 offset0:175 offset1:176
	ds_read2_b32 v[120:121], v139 offset0:173 offset1:174
	v_add_f32_e32 v88, v39, v101
	v_add_f32_e32 v89, v40, v102
	v_add_f32_e32 v90, v41, v103
	s_waitcnt lgkmcnt(1)
	v_add_f32_e32 v119, v92, v119
	v_add_f32_e32 v118, v92, v118
	v_add_f32_e32 v16, v16, v119
	v_add_f32_e32 v17, v17, v118
	s_waitcnt lgkmcnt(0)
	v_add_f32_e32 v119, v92, v121
	v_add_f32_e32 v92, v92, v120
	v_max3_f32 v118, v16, s7, v17
	v_add_f32_e32 v18, v18, v119
	v_add_f32_e32 v19, v19, v92
	v_max3_f32 v92, v118, v18, v19
	v_max3_f32 v85, v92, v20, v21
	v_max3_f32 v85, v85, v22, v23
	v_max3_f32 v24, v85, v7, v6
	v_max3_f32 v24, v24, v5, v4
	v_max3_f32 v24, v24, v25, v26
	v_max3_f32 v24, v24, v27, v28
	v_max3_f32 v24, v24, v29, v30
	v_max3_f32 v24, v24, v31, v32
	v_add_f32_e32 v85, v36, v98
	v_max3_f32 v24, v24, v85, v86
	v_max3_f32 v24, v24, v87, v88
	v_max3_f32 v24, v24, v89, v90
	v_add_f32_e32 v91, v42, v104
	v_add_f32_e32 v92, v43, v105
	v_max3_f32 v24, v24, v91, v92
	v_add_f32_e32 v93, v44, v106
	v_add_f32_e32 v94, v45, v107
	v_max3_f32 v24, v24, v93, v94
	v_add_f32_e32 v95, v46, v108
	v_add_f32_e32 v96, v47, v109
	v_max3_f32 v24, v24, v95, v96
	v_add_f32_e32 v97, v48, v110
	v_add_f32_e32 v49, v49, v111
	v_max3_f32 v24, v24, v97, v49
	v_add_f32_e32 v50, v50, v112
	v_add_f32_e32 v51, v51, v113
	v_max3_f32 v24, v24, v50, v51
	v_add_f32_e32 v0, v0, v114
	v_add_f32_e32 v98, v1, v115
	v_max3_f32 v1, v24, v0, v98
	v_add_f32_e32 v99, v2, v116
	v_add_f32_e32 v100, v3, v117
	v_max3_f32 v1, v1, v99, v100
	ds_bpermute_b32 v2, v140, v1
	v_cvt_pk_bf16_f32 v78, v77, v78
	v_cvt_pk_bf16_f32 v79, v79, v80
	v_cvt_pk_bf16_f32 v80, v81, v82
	v_cvt_pk_bf16_f32 v81, v83, v84
	s_waitcnt lgkmcnt(0)
	v_max_f32_e32 v2, v2, v2
	v_max_f32_e32 v1, v1, v2
	ds_bpermute_b32 v2, v141, v1
	s_waitcnt lgkmcnt(0)
	v_max3_f32 v101, v1, v2, v133
	v_sub_f32_e32 v1, v16, v101
	v_exp_f32_e32 v41, v1
	v_sub_f32_e32 v2, v17, v101
	v_exp_f32_e32 v42, v2
	v_sub_f32_e32 v2, v18, v101
	v_exp_f32_e32 v43, v2
	v_sub_f32_e32 v2, v19, v101
	v_exp_f32_e32 v44, v2
	v_sub_f32_e32 v2, v20, v101
	v_add_f32_e32 v1, 0, v41
	v_exp_f32_e32 v45, v2
	v_sub_f32_e32 v2, v21, v101
	v_add_f32_e32 v1, v42, v1
	v_exp_f32_e32 v46, v2
	v_sub_f32_e32 v2, v22, v101
	v_add_f32_e32 v1, v43, v1
	v_exp_f32_e32 v47, v2
	v_sub_f32_e32 v2, v23, v101
	v_add_f32_e32 v1, v44, v1
	v_exp_f32_e32 v48, v2
	v_sub_f32_e32 v2, v7, v101
	v_add_f32_e32 v1, v45, v1
	v_exp_f32_e32 v33, v2
	v_sub_f32_e32 v2, v6, v101
	v_add_f32_e32 v1, v46, v1
	v_exp_f32_e32 v34, v2
	v_sub_f32_e32 v2, v5, v101
	v_add_f32_e32 v1, v47, v1
	v_exp_f32_e32 v35, v2
	v_sub_f32_e32 v2, v4, v101
	v_add_f32_e32 v1, v48, v1
	v_exp_f32_e32 v36, v2
	v_sub_f32_e32 v2, v25, v101
	v_add_f32_e32 v1, v33, v1
	v_exp_f32_e32 v37, v2
	v_sub_f32_e32 v2, v26, v101
	v_add_f32_e32 v1, v34, v1
	v_exp_f32_e32 v38, v2
	v_sub_f32_e32 v2, v27, v101
	v_add_f32_e32 v1, v35, v1
	v_exp_f32_e32 v39, v2
	v_sub_f32_e32 v2, v28, v101
	v_add_f32_e32 v1, v36, v1
	v_exp_f32_e32 v40, v2
	v_sub_f32_e32 v2, v29, v101
	v_add_f32_e32 v1, v37, v1
	v_exp_f32_e32 v25, v2
	v_sub_f32_e32 v2, v30, v101
	v_add_f32_e32 v1, v38, v1
	v_exp_f32_e32 v26, v2
	v_sub_f32_e32 v2, v31, v101
	v_add_f32_e32 v1, v39, v1
	v_exp_f32_e32 v27, v2
	v_sub_f32_e32 v2, v32, v101
	v_add_f32_e32 v1, v40, v1
	v_exp_f32_e32 v28, v2
	v_sub_f32_e32 v2, v85, v101
	v_add_f32_e32 v1, v25, v1
	v_exp_f32_e32 v29, v2
	v_sub_f32_e32 v2, v86, v101
	v_add_f32_e32 v1, v26, v1
	v_exp_f32_e32 v30, v2
	v_sub_f32_e32 v2, v87, v101
	v_add_f32_e32 v1, v27, v1
	v_exp_f32_e32 v31, v2
	v_sub_f32_e32 v2, v88, v101
	v_add_f32_e32 v1, v28, v1
	v_exp_f32_e32 v32, v2
	v_sub_f32_e32 v2, v89, v101
	v_add_f32_e32 v1, v29, v1
	v_exp_f32_e32 v17, v2
	v_sub_f32_e32 v2, v90, v101
	v_add_f32_e32 v1, v30, v1
	v_exp_f32_e32 v18, v2
	v_sub_f32_e32 v2, v91, v101
	v_add_f32_e32 v1, v31, v1
	v_exp_f32_e32 v19, v2
	v_sub_f32_e32 v2, v92, v101
	v_add_f32_e32 v1, v32, v1
	v_exp_f32_e32 v20, v2
	v_sub_f32_e32 v2, v93, v101
	v_add_f32_e32 v1, v17, v1
	v_exp_f32_e32 v21, v2
	v_sub_f32_e32 v2, v94, v101
	v_add_f32_e32 v1, v18, v1
	v_exp_f32_e32 v22, v2
	v_sub_f32_e32 v2, v95, v101
	v_add_f32_e32 v1, v19, v1
	v_exp_f32_e32 v23, v2
	v_sub_f32_e32 v2, v96, v101
	v_add_f32_e32 v1, v20, v1
	v_exp_f32_e32 v24, v2
	v_add_f32_e32 v1, v21, v1
	v_add_f32_e32 v1, v22, v1
	v_add_f32_e32 v1, v23, v1
	v_add_f32_e32 v2, v24, v1
	v_sub_f32_e32 v1, v97, v101
	v_exp_f32_e32 v1, v1
	v_sub_f32_e32 v0, v0, v101
	v_sub_f32_e32 v7, v99, v101
	v_exp_f32_e32 v7, v7
	v_add_f32_e32 v3, v1, v2
	v_sub_f32_e32 v2, v49, v101
	v_exp_f32_e32 v2, v2
	v_sub_f32_e32 v16, v100, v101
	v_exp_f32_e32 v16, v16
	v_cvt_pk_bf16_f32 v42, v41, v42
	v_add_f32_e32 v4, v2, v3
	v_sub_f32_e32 v3, v50, v101
	v_exp_f32_e32 v3, v3
	v_cvt_pk_bf16_f32 v43, v43, v44
	v_cvt_pk_bf16_f32 v44, v45, v46
	v_cvt_pk_bf16_f32 v45, v47, v48
	ds_read_b128 v[94:97], v142 offset:53952
	ds_read_b128 v[102:105], v142 offset:62400
	v_add_f32_e32 v5, v3, v4
	v_sub_f32_e32 v4, v51, v101
	v_exp_f32_e32 v4, v4
	s_nop 0
	v_add_f32_e32 v6, v4, v5
	v_exp_f32_e32 v5, v0
	s_nop 0
	v_add_f32_e32 v0, v5, v6
	v_sub_f32_e32 v6, v98, v101
	v_exp_f32_e32 v6, v6
	s_nop 0
	v_add_f32_e32 v0, v6, v0
	v_add_f32_e32 v0, v7, v0
	v_add_f32_e32 v0, v16, v0
	ds_bpermute_b32 v49, v140, v0
	s_waitcnt lgkmcnt(0)
	v_add_f32_e32 v0, v0, v49
	ds_bpermute_b32 v49, v141, v0
	s_waitcnt lgkmcnt(0)
	v_add_f32_e32 v0, v0, v49
	v_fma_f32 v49, v162, s6, -v101
	v_exp_f32_e32 v49, v49
	v_mfma_f32_16x16x32_bf16 v[98:101], v[94:97], v[78:81], 0
	v_add_f32_e32 v0, v49, v0
	v_div_scale_f32 v49, s[0:1], v0, v0, 1.0
	v_rcp_f32_e32 v50, v49
	v_mfma_f32_16x16x32_bf16 v[94:97], v[94:97], v[42:45], 0
	v_readlane_b32 s0, v254, 34
	s_add_i32 s29, s29, s0
	v_fma_f32 v51, -v49, v50, 1.0
	v_fmac_f32_e32 v50, v51, v50
	v_div_scale_f32 v51, vcc, 1.0, v0, 1.0
	v_mul_f32_e32 v85, v51, v50
	v_fma_f32 v86, -v49, v85, v51
	v_fmac_f32_e32 v85, v86, v50
	v_fma_f32 v49, -v49, v85, v51
	v_div_fmas_f32 v49, v49, v50, v85
	v_div_fixup_f32 v0, v49, v0, 1.0
	ds_read_b128 v[46:49], v142 offset:37056
	ds_read_b128 v[86:89], v142 offset:45504
	v_cvt_pk_bf16_f32 v70, v69, v70
	v_cvt_pk_bf16_f32 v71, v71, v72
	v_cvt_pk_bf16_f32 v72, v73, v74
	v_cvt_pk_bf16_f32 v73, v75, v76
	v_cvt_pk_bf16_f32 v34, v33, v34
	v_cvt_pk_bf16_f32 v35, v35, v36
	v_cvt_pk_bf16_f32 v36, v37, v38
	v_cvt_pk_bf16_f32 v37, v39, v40
	ds_read_b128 v[38:41], v142 offset:37120
	s_waitcnt lgkmcnt(2)
	v_mfma_f32_16x16x32_bf16 v[82:85], v[46:49], v[78:81], 0
	s_cmpk_lt_i32 s29, 0x100
	s_cselect_b64 s[0:1], -1, 0
	s_cmp_lt_u32 s11, 0x3fffffff
	v_mfma_f32_16x16x32_bf16 v[46:49], v[46:49], v[42:45], 0
	s_cselect_b64 s[6:7], -1, 0
	s_and_b64 s[0:1], s[36:37], s[0:1]
	s_and_b64 s[0:1], s[0:1], s[6:7]
	s_waitcnt lgkmcnt(0)
	v_mfma_f32_16x16x32_bf16 v[74:77], v[38:41], v[70:73], v[82:85]
	v_readlane_b32 s6, v254, 31
	s_add_i32 s28, s28, s6
	s_andn2_b64 vcc, exec, s[0:1]
	v_mfma_f32_16x16x32_bf16 v[38:41], v[38:41], v[34:37], v[46:49]
	s_mov_b32 s11, s20
	s_nop 1
	ds_read_b128 v[46:49], v142 offset:45568
	v_mfma_f32_16x16x32_bf16 v[90:93], v[86:89], v[78:81], 0
	v_mfma_f32_16x16x32_bf16 v[86:89], v[86:89], v[42:45], 0
	s_waitcnt lgkmcnt(0)
	v_mfma_f32_16x16x32_bf16 v[82:85], v[46:49], v[70:73], v[90:93]
	v_mfma_f32_16x16x32_bf16 v[46:49], v[46:49], v[34:37], v[86:89]
	s_nop 4
	ds_read_b128 v[86:89], v142 offset:54016
	s_waitcnt lgkmcnt(0)
	v_mfma_f32_16x16x32_bf16 v[90:93], v[86:89], v[70:73], v[98:101]
	v_mfma_f32_16x16x32_bf16 v[86:89], v[86:89], v[34:37], v[94:97]
	s_nop 2
	ds_read_b128 v[94:97], v142 offset:62464
	v_mfma_f32_16x16x32_bf16 v[42:45], v[102:105], v[42:45], 0
	s_waitcnt lgkmcnt(0)
	v_mfma_f32_16x16x32_bf16 v[34:37], v[94:97], v[34:37], v[42:45]
	v_cvt_pk_bf16_f32 v42, v61, v62
	v_cvt_pk_bf16_f32 v43, v63, v64
	v_cvt_pk_bf16_f32 v44, v65, v66
	v_cvt_pk_bf16_f32 v45, v67, v68
	v_cvt_pk_bf16_f32 v26, v25, v26
	v_cvt_pk_bf16_f32 v27, v27, v28
	v_cvt_pk_bf16_f32 v28, v29, v30
	v_cvt_pk_bf16_f32 v29, v31, v32
	ds_read_b128 v[30:33], v142 offset:37184
	v_mfma_f32_16x16x32_bf16 v[78:81], v[102:105], v[78:81], 0
	v_mfma_f32_16x16x32_bf16 v[70:73], v[94:97], v[70:73], v[78:81]
	s_nop 6
	ds_read_b128 v[78:81], v142 offset:62528
	s_waitcnt lgkmcnt(1)
	v_mfma_f32_16x16x32_bf16 v[62:65], v[30:33], v[42:45], v[74:77]
	v_mfma_f32_16x16x32_bf16 v[30:33], v[30:33], v[26:29], v[38:41]
	s_nop 2
	ds_read_b128 v[38:41], v142 offset:45632
	s_waitcnt lgkmcnt(0)
	v_mfma_f32_16x16x32_bf16 v[66:69], v[38:41], v[42:45], v[82:85]
	v_mfma_f32_16x16x32_bf16 v[38:41], v[38:41], v[26:29], v[46:49]
	s_nop 2
	ds_read_b128 v[46:49], v142 offset:54080
	s_waitcnt lgkmcnt(0)
	v_mfma_f32_16x16x32_bf16 v[74:77], v[46:49], v[42:45], v[90:93]
	v_mfma_f32_16x16x32_bf16 v[46:49], v[46:49], v[26:29], v[86:89]
	v_mfma_f32_16x16x32_bf16 v[26:29], v[78:81], v[26:29], v[34:37]
	v_cvt_pk_bf16_f32 v34, v53, v54
	v_cvt_pk_bf16_f32 v35, v55, v56
	v_cvt_pk_bf16_f32 v36, v57, v58
	v_cvt_pk_bf16_f32 v37, v59, v60
	v_cvt_pk_bf16_f32 v18, v17, v18
	v_cvt_pk_bf16_f32 v19, v19, v20
	v_cvt_pk_bf16_f32 v20, v21, v22
	v_cvt_pk_bf16_f32 v21, v23, v24
	ds_read_b128 v[22:25], v142 offset:37248
	s_waitcnt lgkmcnt(0)
	v_mfma_f32_16x16x32_bf16 v[54:57], v[22:25], v[34:37], v[62:65]
	v_mfma_f32_16x16x32_bf16 v[22:25], v[22:25], v[18:21], v[30:33]
	s_nop 2
	ds_read_b128 v[30:33], v142 offset:45696
	s_waitcnt lgkmcnt(0)
	v_mfma_f32_16x16x32_bf16 v[58:61], v[30:33], v[34:37], v[66:69]
	v_mfma_f32_16x16x32_bf16 v[30:33], v[30:33], v[18:21], v[38:41]
	s_nop 2
	ds_read_b128 v[38:41], v142 offset:54144
	s_waitcnt lgkmcnt(0)
	v_mfma_f32_16x16x32_bf16 v[62:65], v[38:41], v[34:37], v[74:77]
	v_mfma_f32_16x16x32_bf16 v[38:41], v[38:41], v[18:21], v[46:49]
	s_nop 2
	ds_read_b128 v[46:49], v142 offset:62592
	v_cvt_pk_bf16_f32 v10, v9, v10
	v_cvt_pk_bf16_f32 v11, v11, v12
	v_cvt_pk_bf16_f32 v12, v13, v14
	v_cvt_pk_bf16_f32 v13, v15, v52
	v_cvt_pk_bf16_f32 v2, v1, v2
	v_cvt_pk_bf16_f32 v3, v3, v4
	v_cvt_pk_bf16_f32 v4, v5, v6
	v_cvt_pk_bf16_f32 v5, v7, v16
	ds_read_b128 v[14:17], v142 offset:37312
	s_waitcnt lgkmcnt(1)
	v_mfma_f32_16x16x32_bf16 v[18:21], v[46:49], v[18:21], v[26:29]
	v_or_b32_e32 v6, 0x60, v132
	v_ashrrev_i32_e32 v7, 31, v6
	v_lshlrev_b64 v[6:7], 12, v[6:7]
	s_waitcnt lgkmcnt(0)
	v_mfma_f32_16x16x32_bf16 v[26:29], v[14:17], v[10:13], v[54:57]
	v_lshl_add_u64 v[6:7], v[134:135], 0, v[6:7]
	s_nop 6
	v_mfma_f32_16x16x32_bf16 v[14:17], v[14:17], v[2:5], v[22:25]
	s_nop 1
	ds_read_b128 v[22:25], v142 offset:45760
	v_mfma_f32_16x16x32_bf16 v[42:45], v[78:81], v[42:45], v[70:73]
	v_mfma_f32_16x16x32_bf16 v[34:37], v[46:49], v[34:37], v[42:45]
	s_waitcnt lgkmcnt(0)
	v_mfma_f32_16x16x32_bf16 v[42:45], v[22:25], v[10:13], v[58:61]
	v_mfma_f32_16x16x32_bf16 v[22:25], v[22:25], v[2:5], v[30:33]
	s_nop 2
	ds_read_b128 v[30:33], v142 offset:54208
	s_waitcnt lgkmcnt(0)
	v_mfma_f32_16x16x32_bf16 v[46:49], v[30:33], v[10:13], v[62:65]
	v_mfma_f32_16x16x32_bf16 v[30:33], v[30:33], v[2:5], v[38:41]
	s_nop 2
	ds_read_b128 v[38:41], v142 offset:62656
	s_waitcnt lgkmcnt(0)
	v_mfma_f32_16x16x32_bf16 v[2:5], v[38:41], v[2:5], v[18:21]
	v_mfma_f32_16x16x32_bf16 v[10:13], v[38:41], v[10:13], v[34:37]
	v_mul_f32_e32 v26, v8, v26
	v_mul_f32_e32 v27, v8, v27
	v_mul_f32_e32 v28, v8, v28
	v_mul_f32_e32 v29, v8, v29
	v_mul_f32_e32 v42, v8, v42
	v_mul_f32_e32 v43, v8, v43
	v_mul_f32_e32 v44, v8, v44
	v_mul_f32_e32 v45, v8, v45
	v_mul_f32_e32 v46, v8, v46
	v_mul_f32_e32 v47, v8, v47
	v_mul_f32_e32 v48, v8, v48
	v_mul_f32_e32 v49, v8, v49
	v_mul_f32_e32 v10, v8, v10
	v_mul_f32_e32 v11, v8, v11
	v_mul_f32_e32 v12, v8, v12
	v_mul_f32_e32 v13, v8, v13
	v_cvt_pk_bf16_f32 v26, v26, v27
	v_cvt_pk_bf16_f32 v27, v28, v29
	v_cvt_pk_bf16_f32 v28, v42, v43
	v_cvt_pk_bf16_f32 v29, v44, v45
	v_cvt_pk_bf16_f32 v46, v46, v47
	v_cvt_pk_bf16_f32 v47, v48, v49
	v_cvt_pk_bf16_f32 v48, v10, v11
	v_cvt_pk_bf16_f32 v49, v12, v13
	s_nop 1
	v_permlane16_swap_b32_e32 v26, v28
	v_permlane16_swap_b32_e32 v27, v29
	v_permlane16_swap_b32_e32 v46, v48
	v_permlane16_swap_b32_e32 v47, v49
	global_store_dwordx4 v[6:7], v[26:29], off
	global_store_dwordx4 v[6:7], v[46:49], off offset:64
	v_or_b32_e32 v6, 0x70, v132
	v_ashrrev_i32_e32 v7, 31, v6
	v_lshlrev_b64 v[6:7], 12, v[6:7]
	v_lshl_add_u64 v[6:7], v[134:135], 0, v[6:7]
	v_mul_f32_e32 v14, v0, v14
	v_mul_f32_e32 v15, v0, v15
	v_mul_f32_e32 v16, v0, v16
	v_mul_f32_e32 v17, v0, v17
	v_mul_f32_e32 v22, v0, v22
	v_mul_f32_e32 v23, v0, v23
	v_mul_f32_e32 v24, v0, v24
	v_mul_f32_e32 v25, v0, v25
	v_mul_f32_e32 v30, v0, v30
	v_mul_f32_e32 v31, v0, v31
	v_mul_f32_e32 v32, v0, v32
	v_mul_f32_e32 v33, v0, v33
	v_mul_f32_e32 v2, v0, v2
	v_mul_f32_e32 v3, v0, v3
	v_mul_f32_e32 v4, v0, v4
	v_mul_f32_e32 v5, v0, v5
	v_cvt_pk_bf16_f32 v14, v14, v15
	v_cvt_pk_bf16_f32 v15, v16, v17
	v_cvt_pk_bf16_f32 v16, v22, v23
	v_cvt_pk_bf16_f32 v17, v24, v25
	v_cvt_pk_bf16_f32 v30, v30, v31
	v_cvt_pk_bf16_f32 v31, v32, v33
	v_cvt_pk_bf16_f32 v32, v2, v3
	v_cvt_pk_bf16_f32 v33, v4, v5
	s_nop 1
	v_permlane16_swap_b32_e32 v14, v16
	v_permlane16_swap_b32_e32 v15, v17
	v_permlane16_swap_b32_e32 v30, v32
	v_permlane16_swap_b32_e32 v31, v33
	global_store_dwordx4 v[6:7], v[14:17], off
	global_store_dwordx4 v[6:7], v[30:33], off offset:64
	s_barrier
	s_cbranch_vccnz .LBB0_151
